# RWKV scan: per-wave LDS chunk counters replace the per-chunk workgroup barrier between scan and staging waves
# speedup vs baseline: 1.0362x; 1.0026x over previous
.LBB0_649:
	s_and_b64 vcc, exec, s[0:1]
	s_cbranch_vccz .LBB0_676
	s_cmpk_lt_u32 s3, 0x100
	s_mov_b64 s[0:1], -1
	s_cbranch_scc0 .LBB0_654
	v_lshrrev_b32_e32 v1, 4, v152
	v_lshl_or_b32 v1, s50, 2, v1
	v_and_b32_e32 v118, 15, v153
	v_lshlrev_b32_e32 v6, 4, v118
	v_lshlrev_b32_e32 v7, 4, v1
	v_add_u32_e32 v7, 0x23600, v7
	v_lshlrev_b32_e32 v9, 6, v1
	v_lshl_add_u32 v9, v118, 2, v9
	v_add_u32_e32 v9, 0x9b00, v9
	v_mov_b32_e32 v2, 0
	v_mov_b32_e32 v3, 0
	v_mov_b32_e32 v4, 0
	v_mov_b32_e32 v5, 0
	s_mov_b32 s0, 0
	s_mov_b32 s1, 0x11b00
	s_mov_b32 vcc_lo, 0x1000
	s_lshl_b32 vcc_hi, s50, 2
	s_add_i32 vcc_hi, vcc_hi, 0x25610
	v_mov_b32_e32 v16, vcc_hi
	v_mov_b32_e32 v17, 0x25600
	v_mov_b32_e32 v18, 0
	s_mov_b64 exec, 1
	ds_write_b32 v16, v18
	s_mov_b64 exec, -1
	s_waitcnt vmcnt(0) lgkmcnt(0)
	s_barrier
.LBB0_652:
	ds_read_b128 v[20:23], v6 offset:0
	ds_read_b128 v[24:27], v6 offset:256
	ds_read_b128 v[56:59], v7 offset:0
	ds_read_b128 v[28:31], v6 offset:512
	ds_read_b128 v[32:35], v6 offset:768
	ds_read_b128 v[36:39], v6 offset:1024
	ds_read_b128 v[40:43], v6 offset:1280
	ds_read_b128 v[48:51], v6 offset:1792
	ds_read_b128 v[44:47], v6 offset:1536
	ds_read_b128 v[52:55], v6 offset:2048
	s_waitcnt lgkmcnt(9)
	v_pk_mul_f32 v[10:11], v[2:3], v[20:21] op_sel_hi:[0,1]
	ds_read_b128 v[68:71], v6 offset:2304
	s_waitcnt lgkmcnt(8)
	v_pk_fma_f32 v[14:15], v[2:3], v[24:25], v[58:59] op_sel_hi:[0,1,1]
	v_pk_fma_f32 v[10:11], v[2:3], v[22:23], v[10:11] op_sel:[1,0,0] op_sel_hi:[1,1,1]
	ds_read_b128 v[72:75], v6 offset:2560
	v_pk_fma_f32 v[14:15], v[2:3], v[26:27], v[14:15] op_sel:[1,0,0] op_sel_hi:[1,1,1]
	s_waitcnt lgkmcnt(8)
	v_pk_fma_f32 v[10:11], v[4:5], v[28:29], v[10:11] op_sel_hi:[0,1,1]
	s_waitcnt lgkmcnt(7)
	v_pk_fma_f32 v[14:15], v[4:5], v[32:33], v[14:15] op_sel_hi:[0,1,1]
	ds_read_b128 v[104:107], v7 offset:256
	v_pk_fma_f32 v[10:11], v[4:5], v[30:31], v[10:11] op_sel:[1,0,0] op_sel_hi:[1,1,1]
	s_waitcnt lgkmcnt(7)
	v_pk_mul_f32 v[114:115], v[2:3], v[36:37]
	ds_read_b128 v[76:79], v6 offset:2816
	v_pk_mul_f32 v[116:117], v[4:5], v[38:39]
	v_add_f32_dpp v10, v10, v10 row_ror:8 row_mask:0xf bank_mask:0xf bound_ctrl:1
	v_add_f32_dpp v11, v11, v11 row_ror:8 row_mask:0xf bank_mask:0xf bound_ctrl:1
	ds_read_b128 v[80:83], v6 offset:3072
	v_pk_fma_f32 v[14:15], v[4:5], v[34:35], v[14:15] op_sel:[1,0,0] op_sel_hi:[1,1,1]
	v_add_f32_dpp v10, v10, v10 row_ror:4 row_mask:0xf bank_mask:0xf bound_ctrl:1
	ds_read_b128 v[84:87], v6 offset:3328
	v_add_f32_dpp v11, v11, v11 row_ror:4 row_mask:0xf bank_mask:0xf bound_ctrl:1
	s_waitcnt lgkmcnt(9)
	v_pk_fma_f32 v[114:115], v[40:41], v[56:57], v[114:115] op_sel_hi:[1,0,1]
	v_add_f32_dpp v10, v10, v10 row_ror:2 row_mask:0xf bank_mask:0xf bound_ctrl:1
	ds_read_b128 v[88:91], v6 offset:3584
	v_add_f32_dpp v11, v11, v11 row_ror:2 row_mask:0xf bank_mask:0xf bound_ctrl:1
	v_pk_fma_f32 v[116:117], v[42:43], v[56:57], v[116:117] op_sel_hi:[1,0,1]
	ds_read_b128 v[96:99], v6 offset:4096
	v_add_f32_dpp v10, v10, v10 row_ror:1 row_mask:0xf bank_mask:0xf bound_ctrl:1
	v_add_f32_dpp v11, v11, v11 row_ror:1 row_mask:0xf bank_mask:0xf bound_ctrl:1
	s_waitcnt lgkmcnt(10)
	v_pk_fma_f32 v[114:115], v[48:49], v[56:57], v[114:115] op_sel:[0,1,0] op_sel_hi:[1,1,1]
	ds_read_b128 v[92:95], v6 offset:3840
	v_pk_fma_f32 v[116:117], v[50:51], v[56:57], v[116:117] op_sel:[0,1,0] op_sel_hi:[1,1,1]
	s_waitcnt lgkmcnt(10)
	v_pk_fma_f32 v[114:115], v[44:45], v[10:11], v[114:115] op_sel_hi:[1,0,1] neg_lo:[1,0,0] neg_hi:[1,0,0]
	ds_read_b128 v[100:103], v6 offset:4352
	v_pk_fma_f32 v[116:117], v[46:47], v[10:11], v[116:117] op_sel_hi:[1,0,1] neg_lo:[1,0,0] neg_hi:[1,0,0]
	s_waitcnt lgkmcnt(10)
	v_pk_fma_f32 v[2:3], v[52:53], v[10:11], v[114:115] op_sel:[0,1,0] op_sel_hi:[1,1,1] neg_lo:[1,0,0] neg_hi:[1,0,0]
	v_pk_fma_f32 v[4:5], v[54:55], v[10:11], v[116:117] op_sel:[0,1,0] op_sel_hi:[1,1,1] neg_lo:[1,0,0] neg_hi:[1,0,0]
	ds_write2st64_b32 v9, v14, v15 offset0:0 offset1:4
	s_waitcnt lgkmcnt(6)
	v_pk_mul_f32 v[10:11], v[2:3], v[68:69] op_sel_hi:[0,1]
	ds_read_b128 v[20:23], v6 offset:4608
	v_pk_fma_f32 v[14:15], v[2:3], v[72:73], v[106:107] op_sel_hi:[0,1,1]
	v_pk_fma_f32 v[10:11], v[2:3], v[70:71], v[10:11] op_sel:[1,0,0] op_sel_hi:[1,1,1]
	ds_read_b128 v[24:27], v6 offset:4864
	v_pk_fma_f32 v[14:15], v[2:3], v[74:75], v[14:15] op_sel:[1,0,0] op_sel_hi:[1,1,1]
	v_pk_fma_f32 v[10:11], v[4:5], v[76:77], v[10:11] op_sel_hi:[0,1,1]
	v_pk_fma_f32 v[14:15], v[4:5], v[80:81], v[14:15] op_sel_hi:[0,1,1]
	ds_read_b128 v[56:59], v7 offset:512
	v_pk_fma_f32 v[10:11], v[4:5], v[78:79], v[10:11] op_sel:[1,0,0] op_sel_hi:[1,1,1]
	s_waitcnt lgkmcnt(7)
	v_pk_mul_f32 v[114:115], v[2:3], v[84:85]
	ds_read_b128 v[28:31], v6 offset:5120
	v_pk_mul_f32 v[116:117], v[4:5], v[86:87]
	v_add_f32_dpp v10, v10, v10 row_ror:8 row_mask:0xf bank_mask:0xf bound_ctrl:1
	v_add_f32_dpp v11, v11, v11 row_ror:8 row_mask:0xf bank_mask:0xf bound_ctrl:1
	ds_read_b128 v[32:35], v6 offset:5376
	v_pk_fma_f32 v[14:15], v[4:5], v[82:83], v[14:15] op_sel:[1,0,0] op_sel_hi:[1,1,1]
	v_add_f32_dpp v10, v10, v10 row_ror:4 row_mask:0xf bank_mask:0xf bound_ctrl:1
	ds_read_b128 v[36:39], v6 offset:5632
	v_add_f32_dpp v11, v11, v11 row_ror:4 row_mask:0xf bank_mask:0xf bound_ctrl:1
	v_pk_fma_f32 v[114:115], v[88:89], v[104:105], v[114:115] op_sel_hi:[1,0,1]
	v_add_f32_dpp v10, v10, v10 row_ror:2 row_mask:0xf bank_mask:0xf bound_ctrl:1
	ds_read_b128 v[40:43], v6 offset:5888
	v_add_f32_dpp v11, v11, v11 row_ror:2 row_mask:0xf bank_mask:0xf bound_ctrl:1
	v_pk_fma_f32 v[116:117], v[90:91], v[104:105], v[116:117] op_sel_hi:[1,0,1]
	ds_read_b128 v[48:51], v6 offset:6400
	v_add_f32_dpp v10, v10, v10 row_ror:1 row_mask:0xf bank_mask:0xf bound_ctrl:1
	v_add_f32_dpp v11, v11, v11 row_ror:1 row_mask:0xf bank_mask:0xf bound_ctrl:1
	s_waitcnt lgkmcnt(9)
	v_pk_fma_f32 v[114:115], v[96:97], v[104:105], v[114:115] op_sel:[0,1,0] op_sel_hi:[1,1,1]
	ds_read_b128 v[44:47], v6 offset:6144
	v_pk_fma_f32 v[116:117], v[98:99], v[104:105], v[116:117] op_sel:[0,1,0] op_sel_hi:[1,1,1]
	v_pk_fma_f32 v[114:115], v[92:93], v[10:11], v[114:115] op_sel_hi:[1,0,1] neg_lo:[1,0,0] neg_hi:[1,0,0]
	ds_read_b128 v[52:55], v6 offset:6656
	v_pk_fma_f32 v[116:117], v[94:95], v[10:11], v[116:117] op_sel_hi:[1,0,1] neg_lo:[1,0,0] neg_hi:[1,0,0]
	v_pk_fma_f32 v[2:3], v[100:101], v[10:11], v[114:115] op_sel:[0,1,0] op_sel_hi:[1,1,1] neg_lo:[1,0,0] neg_hi:[1,0,0]
	v_pk_fma_f32 v[4:5], v[102:103], v[10:11], v[116:117] op_sel:[0,1,0] op_sel_hi:[1,1,1] neg_lo:[1,0,0] neg_hi:[1,0,0]
	ds_write2st64_b32 v9, v14, v15 offset0:8 offset1:12
	s_waitcnt lgkmcnt(6)
	v_pk_mul_f32 v[10:11], v[2:3], v[20:21] op_sel_hi:[0,1]
	ds_read_b128 v[68:71], v6 offset:6912
	v_pk_fma_f32 v[14:15], v[2:3], v[24:25], v[58:59] op_sel_hi:[0,1,1]
	v_pk_fma_f32 v[10:11], v[2:3], v[22:23], v[10:11] op_sel:[1,0,0] op_sel_hi:[1,1,1]
	ds_read_b128 v[72:75], v6 offset:7168
	v_pk_fma_f32 v[14:15], v[2:3], v[26:27], v[14:15] op_sel:[1,0,0] op_sel_hi:[1,1,1]
	v_pk_fma_f32 v[10:11], v[4:5], v[28:29], v[10:11] op_sel_hi:[0,1,1]
	v_pk_fma_f32 v[14:15], v[4:5], v[32:33], v[14:15] op_sel_hi:[0,1,1]
	ds_read_b128 v[104:107], v7 offset:768
	v_pk_fma_f32 v[10:11], v[4:5], v[30:31], v[10:11] op_sel:[1,0,0] op_sel_hi:[1,1,1]
	s_waitcnt lgkmcnt(7)
	v_pk_mul_f32 v[114:115], v[2:3], v[36:37]
	ds_read_b128 v[76:79], v6 offset:7424
	v_pk_mul_f32 v[116:117], v[4:5], v[38:39]
	v_add_f32_dpp v10, v10, v10 row_ror:8 row_mask:0xf bank_mask:0xf bound_ctrl:1
	v_add_f32_dpp v11, v11, v11 row_ror:8 row_mask:0xf bank_mask:0xf bound_ctrl:1
	ds_read_b128 v[80:83], v6 offset:7680
	v_pk_fma_f32 v[14:15], v[4:5], v[34:35], v[14:15] op_sel:[1,0,0] op_sel_hi:[1,1,1]
	v_add_f32_dpp v10, v10, v10 row_ror:4 row_mask:0xf bank_mask:0xf bound_ctrl:1
	ds_read_b128 v[84:87], v6 offset:7936
	v_add_f32_dpp v11, v11, v11 row_ror:4 row_mask:0xf bank_mask:0xf bound_ctrl:1
	v_pk_fma_f32 v[114:115], v[40:41], v[56:57], v[114:115] op_sel_hi:[1,0,1]
	v_add_f32_dpp v10, v10, v10 row_ror:2 row_mask:0xf bank_mask:0xf bound_ctrl:1
	ds_read_b128 v[88:91], v6 offset:8192
	v_add_f32_dpp v11, v11, v11 row_ror:2 row_mask:0xf bank_mask:0xf bound_ctrl:1
	v_pk_fma_f32 v[116:117], v[42:43], v[56:57], v[116:117] op_sel_hi:[1,0,1]
	ds_read_b128 v[96:99], v6 offset:8704
	v_add_f32_dpp v10, v10, v10 row_ror:1 row_mask:0xf bank_mask:0xf bound_ctrl:1
	v_add_f32_dpp v11, v11, v11 row_ror:1 row_mask:0xf bank_mask:0xf bound_ctrl:1
	s_waitcnt lgkmcnt(9)
	v_pk_fma_f32 v[114:115], v[48:49], v[56:57], v[114:115] op_sel:[0,1,0] op_sel_hi:[1,1,1]
	ds_read_b128 v[92:95], v6 offset:8448
	v_pk_fma_f32 v[116:117], v[50:51], v[56:57], v[116:117] op_sel:[0,1,0] op_sel_hi:[1,1,1]
	v_pk_fma_f32 v[114:115], v[44:45], v[10:11], v[114:115] op_sel_hi:[1,0,1] neg_lo:[1,0,0] neg_hi:[1,0,0]
	ds_read_b128 v[100:103], v6 offset:8960
	v_pk_fma_f32 v[116:117], v[46:47], v[10:11], v[116:117] op_sel_hi:[1,0,1] neg_lo:[1,0,0] neg_hi:[1,0,0]
	v_pk_fma_f32 v[2:3], v[52:53], v[10:11], v[114:115] op_sel:[0,1,0] op_sel_hi:[1,1,1] neg_lo:[1,0,0] neg_hi:[1,0,0]
	v_pk_fma_f32 v[4:5], v[54:55], v[10:11], v[116:117] op_sel:[0,1,0] op_sel_hi:[1,1,1] neg_lo:[1,0,0] neg_hi:[1,0,0]
	ds_write2st64_b32 v9, v14, v15 offset0:16 offset1:20
	s_waitcnt lgkmcnt(6)
	v_pk_mul_f32 v[10:11], v[2:3], v[68:69] op_sel_hi:[0,1]
	ds_read_b128 v[20:23], v6 offset:9216
	v_pk_fma_f32 v[14:15], v[2:3], v[72:73], v[106:107] op_sel_hi:[0,1,1]
	v_pk_fma_f32 v[10:11], v[2:3], v[70:71], v[10:11] op_sel:[1,0,0] op_sel_hi:[1,1,1]
	ds_read_b128 v[24:27], v6 offset:9472
	v_pk_fma_f32 v[14:15], v[2:3], v[74:75], v[14:15] op_sel:[1,0,0] op_sel_hi:[1,1,1]
	v_pk_fma_f32 v[10:11], v[4:5], v[76:77], v[10:11] op_sel_hi:[0,1,1]
	v_pk_fma_f32 v[14:15], v[4:5], v[80:81], v[14:15] op_sel_hi:[0,1,1]
	ds_read_b128 v[56:59], v7 offset:1024
	v_pk_fma_f32 v[10:11], v[4:5], v[78:79], v[10:11] op_sel:[1,0,0] op_sel_hi:[1,1,1]
	s_waitcnt lgkmcnt(7)
	v_pk_mul_f32 v[114:115], v[2:3], v[84:85]
	ds_read_b128 v[28:31], v6 offset:9728
	v_pk_mul_f32 v[116:117], v[4:5], v[86:87]
	v_add_f32_dpp v10, v10, v10 row_ror:8 row_mask:0xf bank_mask:0xf bound_ctrl:1
	v_add_f32_dpp v11, v11, v11 row_ror:8 row_mask:0xf bank_mask:0xf bound_ctrl:1
	ds_read_b128 v[32:35], v6 offset:9984
	v_pk_fma_f32 v[14:15], v[4:5], v[82:83], v[14:15] op_sel:[1,0,0] op_sel_hi:[1,1,1]
	v_add_f32_dpp v10, v10, v10 row_ror:4 row_mask:0xf bank_mask:0xf bound_ctrl:1
	ds_read_b128 v[36:39], v6 offset:10240
	v_add_f32_dpp v11, v11, v11 row_ror:4 row_mask:0xf bank_mask:0xf bound_ctrl:1
	v_pk_fma_f32 v[114:115], v[88:89], v[104:105], v[114:115] op_sel_hi:[1,0,1]
	v_add_f32_dpp v10, v10, v10 row_ror:2 row_mask:0xf bank_mask:0xf bound_ctrl:1
	ds_read_b128 v[40:43], v6 offset:10496
	v_add_f32_dpp v11, v11, v11 row_ror:2 row_mask:0xf bank_mask:0xf bound_ctrl:1
	v_pk_fma_f32 v[116:117], v[90:91], v[104:105], v[116:117] op_sel_hi:[1,0,1]
	ds_read_b128 v[48:51], v6 offset:11008
	v_add_f32_dpp v10, v10, v10 row_ror:1 row_mask:0xf bank_mask:0xf bound_ctrl:1
	v_add_f32_dpp v11, v11, v11 row_ror:1 row_mask:0xf bank_mask:0xf bound_ctrl:1
	s_waitcnt lgkmcnt(9)
	v_pk_fma_f32 v[114:115], v[96:97], v[104:105], v[114:115] op_sel:[0,1,0] op_sel_hi:[1,1,1]
	ds_read_b128 v[44:47], v6 offset:10752
	v_pk_fma_f32 v[116:117], v[98:99], v[104:105], v[116:117] op_sel:[0,1,0] op_sel_hi:[1,1,1]
	v_pk_fma_f32 v[114:115], v[92:93], v[10:11], v[114:115] op_sel_hi:[1,0,1] neg_lo:[1,0,0] neg_hi:[1,0,0]
	ds_read_b128 v[52:55], v6 offset:11264
	v_pk_fma_f32 v[116:117], v[94:95], v[10:11], v[116:117] op_sel_hi:[1,0,1] neg_lo:[1,0,0] neg_hi:[1,0,0]
	v_pk_fma_f32 v[2:3], v[100:101], v[10:11], v[114:115] op_sel:[0,1,0] op_sel_hi:[1,1,1] neg_lo:[1,0,0] neg_hi:[1,0,0]
	v_pk_fma_f32 v[4:5], v[102:103], v[10:11], v[116:117] op_sel:[0,1,0] op_sel_hi:[1,1,1] neg_lo:[1,0,0] neg_hi:[1,0,0]
	ds_write2st64_b32 v9, v14, v15 offset0:24 offset1:28
	s_waitcnt lgkmcnt(6)
	v_pk_mul_f32 v[10:11], v[2:3], v[20:21] op_sel_hi:[0,1]
	ds_read_b128 v[68:71], v6 offset:11520
	v_pk_fma_f32 v[14:15], v[2:3], v[24:25], v[58:59] op_sel_hi:[0,1,1]
	v_pk_fma_f32 v[10:11], v[2:3], v[22:23], v[10:11] op_sel:[1,0,0] op_sel_hi:[1,1,1]
	ds_read_b128 v[72:75], v6 offset:11776
	v_pk_fma_f32 v[14:15], v[2:3], v[26:27], v[14:15] op_sel:[1,0,0] op_sel_hi:[1,1,1]
	v_pk_fma_f32 v[10:11], v[4:5], v[28:29], v[10:11] op_sel_hi:[0,1,1]
	v_pk_fma_f32 v[14:15], v[4:5], v[32:33], v[14:15] op_sel_hi:[0,1,1]
	ds_read_b128 v[104:107], v7 offset:1280
	v_pk_fma_f32 v[10:11], v[4:5], v[30:31], v[10:11] op_sel:[1,0,0] op_sel_hi:[1,1,1]
	s_waitcnt lgkmcnt(7)
	v_pk_mul_f32 v[114:115], v[2:3], v[36:37]
	ds_read_b128 v[76:79], v6 offset:12032
	v_pk_mul_f32 v[116:117], v[4:5], v[38:39]
	v_add_f32_dpp v10, v10, v10 row_ror:8 row_mask:0xf bank_mask:0xf bound_ctrl:1
	v_add_f32_dpp v11, v11, v11 row_ror:8 row_mask:0xf bank_mask:0xf bound_ctrl:1
	ds_read_b128 v[80:83], v6 offset:12288
	v_pk_fma_f32 v[14:15], v[4:5], v[34:35], v[14:15] op_sel:[1,0,0] op_sel_hi:[1,1,1]
	v_add_f32_dpp v10, v10, v10 row_ror:4 row_mask:0xf bank_mask:0xf bound_ctrl:1
	ds_read_b128 v[84:87], v6 offset:12544
	v_add_f32_dpp v11, v11, v11 row_ror:4 row_mask:0xf bank_mask:0xf bound_ctrl:1
	v_pk_fma_f32 v[114:115], v[40:41], v[56:57], v[114:115] op_sel_hi:[1,0,1]
	v_add_f32_dpp v10, v10, v10 row_ror:2 row_mask:0xf bank_mask:0xf bound_ctrl:1
	ds_read_b128 v[88:91], v6 offset:12800
	v_add_f32_dpp v11, v11, v11 row_ror:2 row_mask:0xf bank_mask:0xf bound_ctrl:1
	v_pk_fma_f32 v[116:117], v[42:43], v[56:57], v[116:117] op_sel_hi:[1,0,1]
	ds_read_b128 v[96:99], v6 offset:13312
	v_add_f32_dpp v10, v10, v10 row_ror:1 row_mask:0xf bank_mask:0xf bound_ctrl:1
	v_add_f32_dpp v11, v11, v11 row_ror:1 row_mask:0xf bank_mask:0xf bound_ctrl:1
	s_waitcnt lgkmcnt(9)
	v_pk_fma_f32 v[114:115], v[48:49], v[56:57], v[114:115] op_sel:[0,1,0] op_sel_hi:[1,1,1]
	ds_read_b128 v[92:95], v6 offset:13056
	v_pk_fma_f32 v[116:117], v[50:51], v[56:57], v[116:117] op_sel:[0,1,0] op_sel_hi:[1,1,1]
	v_pk_fma_f32 v[114:115], v[44:45], v[10:11], v[114:115] op_sel_hi:[1,0,1] neg_lo:[1,0,0] neg_hi:[1,0,0]
	ds_read_b128 v[100:103], v6 offset:13568
	v_pk_fma_f32 v[116:117], v[46:47], v[10:11], v[116:117] op_sel_hi:[1,0,1] neg_lo:[1,0,0] neg_hi:[1,0,0]
	v_pk_fma_f32 v[2:3], v[52:53], v[10:11], v[114:115] op_sel:[0,1,0] op_sel_hi:[1,1,1] neg_lo:[1,0,0] neg_hi:[1,0,0]
	v_pk_fma_f32 v[4:5], v[54:55], v[10:11], v[116:117] op_sel:[0,1,0] op_sel_hi:[1,1,1] neg_lo:[1,0,0] neg_hi:[1,0,0]
	ds_write2st64_b32 v9, v14, v15 offset0:32 offset1:36
	s_waitcnt lgkmcnt(6)
	v_pk_mul_f32 v[10:11], v[2:3], v[68:69] op_sel_hi:[0,1]
	ds_read_b128 v[20:23], v6 offset:13824
	v_pk_fma_f32 v[14:15], v[2:3], v[72:73], v[106:107] op_sel_hi:[0,1,1]
	v_pk_fma_f32 v[10:11], v[2:3], v[70:71], v[10:11] op_sel:[1,0,0] op_sel_hi:[1,1,1]
	ds_read_b128 v[24:27], v6 offset:14080
	v_pk_fma_f32 v[14:15], v[2:3], v[74:75], v[14:15] op_sel:[1,0,0] op_sel_hi:[1,1,1]
	v_pk_fma_f32 v[10:11], v[4:5], v[76:77], v[10:11] op_sel_hi:[0,1,1]
	v_pk_fma_f32 v[14:15], v[4:5], v[80:81], v[14:15] op_sel_hi:[0,1,1]
	ds_read_b128 v[56:59], v7 offset:1536
	v_pk_fma_f32 v[10:11], v[4:5], v[78:79], v[10:11] op_sel:[1,0,0] op_sel_hi:[1,1,1]
	s_waitcnt lgkmcnt(7)
	v_pk_mul_f32 v[114:115], v[2:3], v[84:85]
	ds_read_b128 v[28:31], v6 offset:14336
	v_pk_mul_f32 v[116:117], v[4:5], v[86:87]
	v_add_f32_dpp v10, v10, v10 row_ror:8 row_mask:0xf bank_mask:0xf bound_ctrl:1
	v_add_f32_dpp v11, v11, v11 row_ror:8 row_mask:0xf bank_mask:0xf bound_ctrl:1
	ds_read_b128 v[32:35], v6 offset:14592
	v_pk_fma_f32 v[14:15], v[4:5], v[82:83], v[14:15] op_sel:[1,0,0] op_sel_hi:[1,1,1]
	v_add_f32_dpp v10, v10, v10 row_ror:4 row_mask:0xf bank_mask:0xf bound_ctrl:1
	ds_read_b128 v[36:39], v6 offset:14848
	v_add_f32_dpp v11, v11, v11 row_ror:4 row_mask:0xf bank_mask:0xf bound_ctrl:1
	v_pk_fma_f32 v[114:115], v[88:89], v[104:105], v[114:115] op_sel_hi:[1,0,1]
	v_add_f32_dpp v10, v10, v10 row_ror:2 row_mask:0xf bank_mask:0xf bound_ctrl:1
	ds_read_b128 v[40:43], v6 offset:15104
	v_add_f32_dpp v11, v11, v11 row_ror:2 row_mask:0xf bank_mask:0xf bound_ctrl:1
	v_pk_fma_f32 v[116:117], v[90:91], v[104:105], v[116:117] op_sel_hi:[1,0,1]
	ds_read_b128 v[48:51], v6 offset:15616
	v_add_f32_dpp v10, v10, v10 row_ror:1 row_mask:0xf bank_mask:0xf bound_ctrl:1
	v_add_f32_dpp v11, v11, v11 row_ror:1 row_mask:0xf bank_mask:0xf bound_ctrl:1
	s_waitcnt lgkmcnt(9)
	v_pk_fma_f32 v[114:115], v[96:97], v[104:105], v[114:115] op_sel:[0,1,0] op_sel_hi:[1,1,1]
	ds_read_b128 v[44:47], v6 offset:15360
	v_pk_fma_f32 v[116:117], v[98:99], v[104:105], v[116:117] op_sel:[0,1,0] op_sel_hi:[1,1,1]
	v_pk_fma_f32 v[114:115], v[92:93], v[10:11], v[114:115] op_sel_hi:[1,0,1] neg_lo:[1,0,0] neg_hi:[1,0,0]
	ds_read_b128 v[52:55], v6 offset:15872
	v_pk_fma_f32 v[116:117], v[94:95], v[10:11], v[116:117] op_sel_hi:[1,0,1] neg_lo:[1,0,0] neg_hi:[1,0,0]
	v_pk_fma_f32 v[2:3], v[100:101], v[10:11], v[114:115] op_sel:[0,1,0] op_sel_hi:[1,1,1] neg_lo:[1,0,0] neg_hi:[1,0,0]
	v_pk_fma_f32 v[4:5], v[102:103], v[10:11], v[116:117] op_sel:[0,1,0] op_sel_hi:[1,1,1] neg_lo:[1,0,0] neg_hi:[1,0,0]
	ds_write2st64_b32 v9, v14, v15 offset0:40 offset1:44
	s_waitcnt lgkmcnt(6)
	v_pk_mul_f32 v[10:11], v[2:3], v[20:21] op_sel_hi:[0,1]
	ds_read_b128 v[68:71], v6 offset:16128
	v_pk_fma_f32 v[14:15], v[2:3], v[24:25], v[58:59] op_sel_hi:[0,1,1]
	v_pk_fma_f32 v[10:11], v[2:3], v[22:23], v[10:11] op_sel:[1,0,0] op_sel_hi:[1,1,1]
	ds_read_b128 v[72:75], v6 offset:16384
	v_pk_fma_f32 v[14:15], v[2:3], v[26:27], v[14:15] op_sel:[1,0,0] op_sel_hi:[1,1,1]
	v_pk_fma_f32 v[10:11], v[4:5], v[28:29], v[10:11] op_sel_hi:[0,1,1]
	v_pk_fma_f32 v[14:15], v[4:5], v[32:33], v[14:15] op_sel_hi:[0,1,1]
	ds_read_b128 v[104:107], v7 offset:1792
	v_pk_fma_f32 v[10:11], v[4:5], v[30:31], v[10:11] op_sel:[1,0,0] op_sel_hi:[1,1,1]
	s_waitcnt lgkmcnt(7)
	v_pk_mul_f32 v[114:115], v[2:3], v[36:37]
	ds_read_b128 v[76:79], v6 offset:16640
	v_pk_mul_f32 v[116:117], v[4:5], v[38:39]
	v_add_f32_dpp v10, v10, v10 row_ror:8 row_mask:0xf bank_mask:0xf bound_ctrl:1
	v_add_f32_dpp v11, v11, v11 row_ror:8 row_mask:0xf bank_mask:0xf bound_ctrl:1
	ds_read_b128 v[80:83], v6 offset:16896
	v_pk_fma_f32 v[14:15], v[4:5], v[34:35], v[14:15] op_sel:[1,0,0] op_sel_hi:[1,1,1]
	v_add_f32_dpp v10, v10, v10 row_ror:4 row_mask:0xf bank_mask:0xf bound_ctrl:1
	ds_read_b128 v[84:87], v6 offset:17152
	v_add_f32_dpp v11, v11, v11 row_ror:4 row_mask:0xf bank_mask:0xf bound_ctrl:1
	v_pk_fma_f32 v[114:115], v[40:41], v[56:57], v[114:115] op_sel_hi:[1,0,1]
	v_add_f32_dpp v10, v10, v10 row_ror:2 row_mask:0xf bank_mask:0xf bound_ctrl:1
	ds_read_b128 v[88:91], v6 offset:17408
	v_add_f32_dpp v11, v11, v11 row_ror:2 row_mask:0xf bank_mask:0xf bound_ctrl:1
	v_pk_fma_f32 v[116:117], v[42:43], v[56:57], v[116:117] op_sel_hi:[1,0,1]
	ds_read_b128 v[96:99], v6 offset:17920
	v_add_f32_dpp v10, v10, v10 row_ror:1 row_mask:0xf bank_mask:0xf bound_ctrl:1
	v_add_f32_dpp v11, v11, v11 row_ror:1 row_mask:0xf bank_mask:0xf bound_ctrl:1
	s_waitcnt lgkmcnt(9)
	v_pk_fma_f32 v[114:115], v[48:49], v[56:57], v[114:115] op_sel:[0,1,0] op_sel_hi:[1,1,1]
	ds_read_b128 v[92:95], v6 offset:17664
	v_pk_fma_f32 v[116:117], v[50:51], v[56:57], v[116:117] op_sel:[0,1,0] op_sel_hi:[1,1,1]
	v_pk_fma_f32 v[114:115], v[44:45], v[10:11], v[114:115] op_sel_hi:[1,0,1] neg_lo:[1,0,0] neg_hi:[1,0,0]
	ds_read_b128 v[100:103], v6 offset:18176
	v_pk_fma_f32 v[116:117], v[46:47], v[10:11], v[116:117] op_sel_hi:[1,0,1] neg_lo:[1,0,0] neg_hi:[1,0,0]
	v_pk_fma_f32 v[2:3], v[52:53], v[10:11], v[114:115] op_sel:[0,1,0] op_sel_hi:[1,1,1] neg_lo:[1,0,0] neg_hi:[1,0,0]
	v_pk_fma_f32 v[4:5], v[54:55], v[10:11], v[116:117] op_sel:[0,1,0] op_sel_hi:[1,1,1] neg_lo:[1,0,0] neg_hi:[1,0,0]
	ds_write2st64_b32 v9, v14, v15 offset0:48 offset1:52
	s_waitcnt lgkmcnt(6)
	v_pk_mul_f32 v[10:11], v[2:3], v[68:69] op_sel_hi:[0,1]
	ds_read_b128 v[20:23], v6 offset:18432
	v_pk_fma_f32 v[14:15], v[2:3], v[72:73], v[106:107] op_sel_hi:[0,1,1]
	v_pk_fma_f32 v[10:11], v[2:3], v[70:71], v[10:11] op_sel:[1,0,0] op_sel_hi:[1,1,1]
	ds_read_b128 v[24:27], v6 offset:18688
	v_pk_fma_f32 v[14:15], v[2:3], v[74:75], v[14:15] op_sel:[1,0,0] op_sel_hi:[1,1,1]
	v_pk_fma_f32 v[10:11], v[4:5], v[76:77], v[10:11] op_sel_hi:[0,1,1]
	v_pk_fma_f32 v[14:15], v[4:5], v[80:81], v[14:15] op_sel_hi:[0,1,1]
	ds_read_b128 v[56:59], v7 offset:2048
	v_pk_fma_f32 v[10:11], v[4:5], v[78:79], v[10:11] op_sel:[1,0,0] op_sel_hi:[1,1,1]
	s_waitcnt lgkmcnt(7)
	v_pk_mul_f32 v[114:115], v[2:3], v[84:85]
	ds_read_b128 v[28:31], v6 offset:18944
	v_pk_mul_f32 v[116:117], v[4:5], v[86:87]
	v_add_f32_dpp v10, v10, v10 row_ror:8 row_mask:0xf bank_mask:0xf bound_ctrl:1
	v_add_f32_dpp v11, v11, v11 row_ror:8 row_mask:0xf bank_mask:0xf bound_ctrl:1
	ds_read_b128 v[32:35], v6 offset:19200
	v_pk_fma_f32 v[14:15], v[4:5], v[82:83], v[14:15] op_sel:[1,0,0] op_sel_hi:[1,1,1]
	v_add_f32_dpp v10, v10, v10 row_ror:4 row_mask:0xf bank_mask:0xf bound_ctrl:1
	ds_read_b128 v[36:39], v6 offset:19456
	v_add_f32_dpp v11, v11, v11 row_ror:4 row_mask:0xf bank_mask:0xf bound_ctrl:1
	v_pk_fma_f32 v[114:115], v[88:89], v[104:105], v[114:115] op_sel_hi:[1,0,1]
	v_add_f32_dpp v10, v10, v10 row_ror:2 row_mask:0xf bank_mask:0xf bound_ctrl:1
	ds_read_b128 v[40:43], v6 offset:19712
	v_add_f32_dpp v11, v11, v11 row_ror:2 row_mask:0xf bank_mask:0xf bound_ctrl:1
	v_pk_fma_f32 v[116:117], v[90:91], v[104:105], v[116:117] op_sel_hi:[1,0,1]
	ds_read_b128 v[48:51], v6 offset:20224
	v_add_f32_dpp v10, v10, v10 row_ror:1 row_mask:0xf bank_mask:0xf bound_ctrl:1
	v_add_f32_dpp v11, v11, v11 row_ror:1 row_mask:0xf bank_mask:0xf bound_ctrl:1
	s_waitcnt lgkmcnt(9)
	v_pk_fma_f32 v[114:115], v[96:97], v[104:105], v[114:115] op_sel:[0,1,0] op_sel_hi:[1,1,1]
	ds_read_b128 v[44:47], v6 offset:19968
	v_pk_fma_f32 v[116:117], v[98:99], v[104:105], v[116:117] op_sel:[0,1,0] op_sel_hi:[1,1,1]
	v_pk_fma_f32 v[114:115], v[92:93], v[10:11], v[114:115] op_sel_hi:[1,0,1] neg_lo:[1,0,0] neg_hi:[1,0,0]
	ds_read_b128 v[52:55], v6 offset:20480
	v_pk_fma_f32 v[116:117], v[94:95], v[10:11], v[116:117] op_sel_hi:[1,0,1] neg_lo:[1,0,0] neg_hi:[1,0,0]
	v_pk_fma_f32 v[2:3], v[100:101], v[10:11], v[114:115] op_sel:[0,1,0] op_sel_hi:[1,1,1] neg_lo:[1,0,0] neg_hi:[1,0,0]
	v_pk_fma_f32 v[4:5], v[102:103], v[10:11], v[116:117] op_sel:[0,1,0] op_sel_hi:[1,1,1] neg_lo:[1,0,0] neg_hi:[1,0,0]
	ds_write2st64_b32 v9, v14, v15 offset0:56 offset1:60
	s_waitcnt lgkmcnt(6)
	v_pk_mul_f32 v[10:11], v[2:3], v[20:21] op_sel_hi:[0,1]
	ds_read_b128 v[68:71], v6 offset:20736
	v_pk_fma_f32 v[14:15], v[2:3], v[24:25], v[58:59] op_sel_hi:[0,1,1]
	v_pk_fma_f32 v[10:11], v[2:3], v[22:23], v[10:11] op_sel:[1,0,0] op_sel_hi:[1,1,1]
	ds_read_b128 v[72:75], v6 offset:20992
	v_pk_fma_f32 v[14:15], v[2:3], v[26:27], v[14:15] op_sel:[1,0,0] op_sel_hi:[1,1,1]
	v_pk_fma_f32 v[10:11], v[4:5], v[28:29], v[10:11] op_sel_hi:[0,1,1]
	v_pk_fma_f32 v[14:15], v[4:5], v[32:33], v[14:15] op_sel_hi:[0,1,1]
	ds_read_b128 v[104:107], v7 offset:2304
	v_pk_fma_f32 v[10:11], v[4:5], v[30:31], v[10:11] op_sel:[1,0,0] op_sel_hi:[1,1,1]
	s_waitcnt lgkmcnt(7)
	v_pk_mul_f32 v[114:115], v[2:3], v[36:37]
	ds_read_b128 v[76:79], v6 offset:21248
	v_pk_mul_f32 v[116:117], v[4:5], v[38:39]
	v_add_f32_dpp v10, v10, v10 row_ror:8 row_mask:0xf bank_mask:0xf bound_ctrl:1
	v_add_f32_dpp v11, v11, v11 row_ror:8 row_mask:0xf bank_mask:0xf bound_ctrl:1
	ds_read_b128 v[80:83], v6 offset:21504
	v_pk_fma_f32 v[14:15], v[4:5], v[34:35], v[14:15] op_sel:[1,0,0] op_sel_hi:[1,1,1]
	v_add_f32_dpp v10, v10, v10 row_ror:4 row_mask:0xf bank_mask:0xf bound_ctrl:1
	ds_read_b128 v[84:87], v6 offset:21760
	v_add_f32_dpp v11, v11, v11 row_ror:4 row_mask:0xf bank_mask:0xf bound_ctrl:1
	v_pk_fma_f32 v[114:115], v[40:41], v[56:57], v[114:115] op_sel_hi:[1,0,1]
	v_add_f32_dpp v10, v10, v10 row_ror:2 row_mask:0xf bank_mask:0xf bound_ctrl:1
	ds_read_b128 v[88:91], v6 offset:22016
	v_add_f32_dpp v11, v11, v11 row_ror:2 row_mask:0xf bank_mask:0xf bound_ctrl:1
	v_pk_fma_f32 v[116:117], v[42:43], v[56:57], v[116:117] op_sel_hi:[1,0,1]
	ds_read_b128 v[96:99], v6 offset:22528
	v_add_f32_dpp v10, v10, v10 row_ror:1 row_mask:0xf bank_mask:0xf bound_ctrl:1
	v_add_f32_dpp v11, v11, v11 row_ror:1 row_mask:0xf bank_mask:0xf bound_ctrl:1
	s_waitcnt lgkmcnt(9)
	v_pk_fma_f32 v[114:115], v[48:49], v[56:57], v[114:115] op_sel:[0,1,0] op_sel_hi:[1,1,1]
	ds_read_b128 v[92:95], v6 offset:22272
	v_pk_fma_f32 v[116:117], v[50:51], v[56:57], v[116:117] op_sel:[0,1,0] op_sel_hi:[1,1,1]
	v_pk_fma_f32 v[114:115], v[44:45], v[10:11], v[114:115] op_sel_hi:[1,0,1] neg_lo:[1,0,0] neg_hi:[1,0,0]
	ds_read_b128 v[100:103], v6 offset:22784
	v_pk_fma_f32 v[116:117], v[46:47], v[10:11], v[116:117] op_sel_hi:[1,0,1] neg_lo:[1,0,0] neg_hi:[1,0,0]
	v_pk_fma_f32 v[2:3], v[52:53], v[10:11], v[114:115] op_sel:[0,1,0] op_sel_hi:[1,1,1] neg_lo:[1,0,0] neg_hi:[1,0,0]
	v_pk_fma_f32 v[4:5], v[54:55], v[10:11], v[116:117] op_sel:[0,1,0] op_sel_hi:[1,1,1] neg_lo:[1,0,0] neg_hi:[1,0,0]
	ds_write2st64_b32 v9, v14, v15 offset0:64 offset1:68
	s_waitcnt lgkmcnt(6)
	v_pk_mul_f32 v[10:11], v[2:3], v[68:69] op_sel_hi:[0,1]
	ds_read_b128 v[20:23], v6 offset:23040
	v_pk_fma_f32 v[14:15], v[2:3], v[72:73], v[106:107] op_sel_hi:[0,1,1]
	v_pk_fma_f32 v[10:11], v[2:3], v[70:71], v[10:11] op_sel:[1,0,0] op_sel_hi:[1,1,1]
	ds_read_b128 v[24:27], v6 offset:23296
	v_pk_fma_f32 v[14:15], v[2:3], v[74:75], v[14:15] op_sel:[1,0,0] op_sel_hi:[1,1,1]
	v_pk_fma_f32 v[10:11], v[4:5], v[76:77], v[10:11] op_sel_hi:[0,1,1]
	v_pk_fma_f32 v[14:15], v[4:5], v[80:81], v[14:15] op_sel_hi:[0,1,1]
	ds_read_b128 v[56:59], v7 offset:2560
	v_pk_fma_f32 v[10:11], v[4:5], v[78:79], v[10:11] op_sel:[1,0,0] op_sel_hi:[1,1,1]
	s_waitcnt lgkmcnt(7)
	v_pk_mul_f32 v[114:115], v[2:3], v[84:85]
	ds_read_b128 v[28:31], v6 offset:23552
	v_pk_mul_f32 v[116:117], v[4:5], v[86:87]
	v_add_f32_dpp v10, v10, v10 row_ror:8 row_mask:0xf bank_mask:0xf bound_ctrl:1
	v_add_f32_dpp v11, v11, v11 row_ror:8 row_mask:0xf bank_mask:0xf bound_ctrl:1
	ds_read_b128 v[32:35], v6 offset:23808
	v_pk_fma_f32 v[14:15], v[4:5], v[82:83], v[14:15] op_sel:[1,0,0] op_sel_hi:[1,1,1]
	v_add_f32_dpp v10, v10, v10 row_ror:4 row_mask:0xf bank_mask:0xf bound_ctrl:1
	ds_read_b128 v[36:39], v6 offset:24064
	v_add_f32_dpp v11, v11, v11 row_ror:4 row_mask:0xf bank_mask:0xf bound_ctrl:1
	v_pk_fma_f32 v[114:115], v[88:89], v[104:105], v[114:115] op_sel_hi:[1,0,1]
	v_add_f32_dpp v10, v10, v10 row_ror:2 row_mask:0xf bank_mask:0xf bound_ctrl:1
	ds_read_b128 v[40:43], v6 offset:24320
	v_add_f32_dpp v11, v11, v11 row_ror:2 row_mask:0xf bank_mask:0xf bound_ctrl:1
	v_pk_fma_f32 v[116:117], v[90:91], v[104:105], v[116:117] op_sel_hi:[1,0,1]
	ds_read_b128 v[48:51], v6 offset:24832
	v_add_f32_dpp v10, v10, v10 row_ror:1 row_mask:0xf bank_mask:0xf bound_ctrl:1
	v_add_f32_dpp v11, v11, v11 row_ror:1 row_mask:0xf bank_mask:0xf bound_ctrl:1
	s_waitcnt lgkmcnt(9)
	v_pk_fma_f32 v[114:115], v[96:97], v[104:105], v[114:115] op_sel:[0,1,0] op_sel_hi:[1,1,1]
	ds_read_b128 v[44:47], v6 offset:24576
	v_pk_fma_f32 v[116:117], v[98:99], v[104:105], v[116:117] op_sel:[0,1,0] op_sel_hi:[1,1,1]
	v_pk_fma_f32 v[114:115], v[92:93], v[10:11], v[114:115] op_sel_hi:[1,0,1] neg_lo:[1,0,0] neg_hi:[1,0,0]
	ds_read_b128 v[52:55], v6 offset:25088
	v_pk_fma_f32 v[116:117], v[94:95], v[10:11], v[116:117] op_sel_hi:[1,0,1] neg_lo:[1,0,0] neg_hi:[1,0,0]
	v_pk_fma_f32 v[2:3], v[100:101], v[10:11], v[114:115] op_sel:[0,1,0] op_sel_hi:[1,1,1] neg_lo:[1,0,0] neg_hi:[1,0,0]
	v_pk_fma_f32 v[4:5], v[102:103], v[10:11], v[116:117] op_sel:[0,1,0] op_sel_hi:[1,1,1] neg_lo:[1,0,0] neg_hi:[1,0,0]
	ds_write2st64_b32 v9, v14, v15 offset0:72 offset1:76
	s_waitcnt lgkmcnt(6)
	v_pk_mul_f32 v[10:11], v[2:3], v[20:21] op_sel_hi:[0,1]
	ds_read_b128 v[68:71], v6 offset:25344
	v_pk_fma_f32 v[14:15], v[2:3], v[24:25], v[58:59] op_sel_hi:[0,1,1]
	v_pk_fma_f32 v[10:11], v[2:3], v[22:23], v[10:11] op_sel:[1,0,0] op_sel_hi:[1,1,1]
	ds_read_b128 v[72:75], v6 offset:25600
	v_pk_fma_f32 v[14:15], v[2:3], v[26:27], v[14:15] op_sel:[1,0,0] op_sel_hi:[1,1,1]
	v_pk_fma_f32 v[10:11], v[4:5], v[28:29], v[10:11] op_sel_hi:[0,1,1]
	v_pk_fma_f32 v[14:15], v[4:5], v[32:33], v[14:15] op_sel_hi:[0,1,1]
	ds_read_b128 v[104:107], v7 offset:2816
	v_pk_fma_f32 v[10:11], v[4:5], v[30:31], v[10:11] op_sel:[1,0,0] op_sel_hi:[1,1,1]
	s_waitcnt lgkmcnt(7)
	v_pk_mul_f32 v[114:115], v[2:3], v[36:37]
	ds_read_b128 v[76:79], v6 offset:25856
	v_pk_mul_f32 v[116:117], v[4:5], v[38:39]
	v_add_f32_dpp v10, v10, v10 row_ror:8 row_mask:0xf bank_mask:0xf bound_ctrl:1
	v_add_f32_dpp v11, v11, v11 row_ror:8 row_mask:0xf bank_mask:0xf bound_ctrl:1
	ds_read_b128 v[80:83], v6 offset:26112
	v_pk_fma_f32 v[14:15], v[4:5], v[34:35], v[14:15] op_sel:[1,0,0] op_sel_hi:[1,1,1]
	v_add_f32_dpp v10, v10, v10 row_ror:4 row_mask:0xf bank_mask:0xf bound_ctrl:1
	ds_read_b128 v[84:87], v6 offset:26368
	v_add_f32_dpp v11, v11, v11 row_ror:4 row_mask:0xf bank_mask:0xf bound_ctrl:1
	v_pk_fma_f32 v[114:115], v[40:41], v[56:57], v[114:115] op_sel_hi:[1,0,1]
	v_add_f32_dpp v10, v10, v10 row_ror:2 row_mask:0xf bank_mask:0xf bound_ctrl:1
	ds_read_b128 v[88:91], v6 offset:26624
	v_add_f32_dpp v11, v11, v11 row_ror:2 row_mask:0xf bank_mask:0xf bound_ctrl:1
	v_pk_fma_f32 v[116:117], v[42:43], v[56:57], v[116:117] op_sel_hi:[1,0,1]
	ds_read_b128 v[96:99], v6 offset:27136
	v_add_f32_dpp v10, v10, v10 row_ror:1 row_mask:0xf bank_mask:0xf bound_ctrl:1
	v_add_f32_dpp v11, v11, v11 row_ror:1 row_mask:0xf bank_mask:0xf bound_ctrl:1
	s_waitcnt lgkmcnt(9)
	v_pk_fma_f32 v[114:115], v[48:49], v[56:57], v[114:115] op_sel:[0,1,0] op_sel_hi:[1,1,1]
	ds_read_b128 v[92:95], v6 offset:26880
	v_pk_fma_f32 v[116:117], v[50:51], v[56:57], v[116:117] op_sel:[0,1,0] op_sel_hi:[1,1,1]
	v_pk_fma_f32 v[114:115], v[44:45], v[10:11], v[114:115] op_sel_hi:[1,0,1] neg_lo:[1,0,0] neg_hi:[1,0,0]
	ds_read_b128 v[100:103], v6 offset:27392
	v_pk_fma_f32 v[116:117], v[46:47], v[10:11], v[116:117] op_sel_hi:[1,0,1] neg_lo:[1,0,0] neg_hi:[1,0,0]
	v_pk_fma_f32 v[2:3], v[52:53], v[10:11], v[114:115] op_sel:[0,1,0] op_sel_hi:[1,1,1] neg_lo:[1,0,0] neg_hi:[1,0,0]
	v_pk_fma_f32 v[4:5], v[54:55], v[10:11], v[116:117] op_sel:[0,1,0] op_sel_hi:[1,1,1] neg_lo:[1,0,0] neg_hi:[1,0,0]
	ds_write2st64_b32 v9, v14, v15 offset0:80 offset1:84
	s_waitcnt lgkmcnt(6)
	v_pk_mul_f32 v[10:11], v[2:3], v[68:69] op_sel_hi:[0,1]
	ds_read_b128 v[20:23], v6 offset:27648
	v_pk_fma_f32 v[14:15], v[2:3], v[72:73], v[106:107] op_sel_hi:[0,1,1]
	v_pk_fma_f32 v[10:11], v[2:3], v[70:71], v[10:11] op_sel:[1,0,0] op_sel_hi:[1,1,1]
	ds_read_b128 v[24:27], v6 offset:27904
	v_pk_fma_f32 v[14:15], v[2:3], v[74:75], v[14:15] op_sel:[1,0,0] op_sel_hi:[1,1,1]
	v_pk_fma_f32 v[10:11], v[4:5], v[76:77], v[10:11] op_sel_hi:[0,1,1]
	v_pk_fma_f32 v[14:15], v[4:5], v[80:81], v[14:15] op_sel_hi:[0,1,1]
	ds_read_b128 v[56:59], v7 offset:3072
	v_pk_fma_f32 v[10:11], v[4:5], v[78:79], v[10:11] op_sel:[1,0,0] op_sel_hi:[1,1,1]
	s_waitcnt lgkmcnt(7)
	v_pk_mul_f32 v[114:115], v[2:3], v[84:85]
	ds_read_b128 v[28:31], v6 offset:28160
	v_pk_mul_f32 v[116:117], v[4:5], v[86:87]
	v_add_f32_dpp v10, v10, v10 row_ror:8 row_mask:0xf bank_mask:0xf bound_ctrl:1
	v_add_f32_dpp v11, v11, v11 row_ror:8 row_mask:0xf bank_mask:0xf bound_ctrl:1
	ds_read_b128 v[32:35], v6 offset:28416
	v_pk_fma_f32 v[14:15], v[4:5], v[82:83], v[14:15] op_sel:[1,0,0] op_sel_hi:[1,1,1]
	v_add_f32_dpp v10, v10, v10 row_ror:4 row_mask:0xf bank_mask:0xf bound_ctrl:1
	ds_read_b128 v[36:39], v6 offset:28672
	v_add_f32_dpp v11, v11, v11 row_ror:4 row_mask:0xf bank_mask:0xf bound_ctrl:1
	v_pk_fma_f32 v[114:115], v[88:89], v[104:105], v[114:115] op_sel_hi:[1,0,1]
	v_add_f32_dpp v10, v10, v10 row_ror:2 row_mask:0xf bank_mask:0xf bound_ctrl:1
	ds_read_b128 v[40:43], v6 offset:28928
	v_add_f32_dpp v11, v11, v11 row_ror:2 row_mask:0xf bank_mask:0xf bound_ctrl:1
	v_pk_fma_f32 v[116:117], v[90:91], v[104:105], v[116:117] op_sel_hi:[1,0,1]
	ds_read_b128 v[48:51], v6 offset:29440
	v_add_f32_dpp v10, v10, v10 row_ror:1 row_mask:0xf bank_mask:0xf bound_ctrl:1
	v_add_f32_dpp v11, v11, v11 row_ror:1 row_mask:0xf bank_mask:0xf bound_ctrl:1
	s_waitcnt lgkmcnt(9)
	v_pk_fma_f32 v[114:115], v[96:97], v[104:105], v[114:115] op_sel:[0,1,0] op_sel_hi:[1,1,1]
	ds_read_b128 v[44:47], v6 offset:29184
	v_pk_fma_f32 v[116:117], v[98:99], v[104:105], v[116:117] op_sel:[0,1,0] op_sel_hi:[1,1,1]
	v_pk_fma_f32 v[114:115], v[92:93], v[10:11], v[114:115] op_sel_hi:[1,0,1] neg_lo:[1,0,0] neg_hi:[1,0,0]
	ds_read_b128 v[52:55], v6 offset:29696
	v_pk_fma_f32 v[116:117], v[94:95], v[10:11], v[116:117] op_sel_hi:[1,0,1] neg_lo:[1,0,0] neg_hi:[1,0,0]
	v_pk_fma_f32 v[2:3], v[100:101], v[10:11], v[114:115] op_sel:[0,1,0] op_sel_hi:[1,1,1] neg_lo:[1,0,0] neg_hi:[1,0,0]
	v_pk_fma_f32 v[4:5], v[102:103], v[10:11], v[116:117] op_sel:[0,1,0] op_sel_hi:[1,1,1] neg_lo:[1,0,0] neg_hi:[1,0,0]
	ds_write2st64_b32 v9, v14, v15 offset0:88 offset1:92
	s_waitcnt lgkmcnt(6)
	v_pk_mul_f32 v[10:11], v[2:3], v[20:21] op_sel_hi:[0,1]
	ds_read_b128 v[68:71], v6 offset:29952
	v_pk_fma_f32 v[14:15], v[2:3], v[24:25], v[58:59] op_sel_hi:[0,1,1]
	v_pk_fma_f32 v[10:11], v[2:3], v[22:23], v[10:11] op_sel:[1,0,0] op_sel_hi:[1,1,1]
	ds_read_b128 v[72:75], v6 offset:30208
	v_pk_fma_f32 v[14:15], v[2:3], v[26:27], v[14:15] op_sel:[1,0,0] op_sel_hi:[1,1,1]
	v_pk_fma_f32 v[10:11], v[4:5], v[28:29], v[10:11] op_sel_hi:[0,1,1]
	v_pk_fma_f32 v[14:15], v[4:5], v[32:33], v[14:15] op_sel_hi:[0,1,1]
	ds_read_b128 v[104:107], v7 offset:3328
	v_pk_fma_f32 v[10:11], v[4:5], v[30:31], v[10:11] op_sel:[1,0,0] op_sel_hi:[1,1,1]
	s_waitcnt lgkmcnt(7)
	v_pk_mul_f32 v[114:115], v[2:3], v[36:37]
	ds_read_b128 v[76:79], v6 offset:30464
	v_pk_mul_f32 v[116:117], v[4:5], v[38:39]
	v_add_f32_dpp v10, v10, v10 row_ror:8 row_mask:0xf bank_mask:0xf bound_ctrl:1
	v_add_f32_dpp v11, v11, v11 row_ror:8 row_mask:0xf bank_mask:0xf bound_ctrl:1
	ds_read_b128 v[80:83], v6 offset:30720
	v_pk_fma_f32 v[14:15], v[4:5], v[34:35], v[14:15] op_sel:[1,0,0] op_sel_hi:[1,1,1]
	v_add_f32_dpp v10, v10, v10 row_ror:4 row_mask:0xf bank_mask:0xf bound_ctrl:1
	ds_read_b128 v[84:87], v6 offset:30976
	v_add_f32_dpp v11, v11, v11 row_ror:4 row_mask:0xf bank_mask:0xf bound_ctrl:1
	v_pk_fma_f32 v[114:115], v[40:41], v[56:57], v[114:115] op_sel_hi:[1,0,1]
	v_add_f32_dpp v10, v10, v10 row_ror:2 row_mask:0xf bank_mask:0xf bound_ctrl:1
	ds_read_b128 v[88:91], v6 offset:31232
	v_add_f32_dpp v11, v11, v11 row_ror:2 row_mask:0xf bank_mask:0xf bound_ctrl:1
	v_pk_fma_f32 v[116:117], v[42:43], v[56:57], v[116:117] op_sel_hi:[1,0,1]
	ds_read_b128 v[96:99], v6 offset:31744
	v_add_f32_dpp v10, v10, v10 row_ror:1 row_mask:0xf bank_mask:0xf bound_ctrl:1
	v_add_f32_dpp v11, v11, v11 row_ror:1 row_mask:0xf bank_mask:0xf bound_ctrl:1
	s_waitcnt lgkmcnt(9)
	v_pk_fma_f32 v[114:115], v[48:49], v[56:57], v[114:115] op_sel:[0,1,0] op_sel_hi:[1,1,1]
	ds_read_b128 v[92:95], v6 offset:31488
	v_pk_fma_f32 v[116:117], v[50:51], v[56:57], v[116:117] op_sel:[0,1,0] op_sel_hi:[1,1,1]
	v_pk_fma_f32 v[114:115], v[44:45], v[10:11], v[114:115] op_sel_hi:[1,0,1] neg_lo:[1,0,0] neg_hi:[1,0,0]
	ds_read_b128 v[100:103], v6 offset:32000
	v_pk_fma_f32 v[116:117], v[46:47], v[10:11], v[116:117] op_sel_hi:[1,0,1] neg_lo:[1,0,0] neg_hi:[1,0,0]
	v_pk_fma_f32 v[2:3], v[52:53], v[10:11], v[114:115] op_sel:[0,1,0] op_sel_hi:[1,1,1] neg_lo:[1,0,0] neg_hi:[1,0,0]
	v_pk_fma_f32 v[4:5], v[54:55], v[10:11], v[116:117] op_sel:[0,1,0] op_sel_hi:[1,1,1] neg_lo:[1,0,0] neg_hi:[1,0,0]
	ds_write2st64_b32 v9, v14, v15 offset0:96 offset1:100
	s_waitcnt lgkmcnt(6)
	v_pk_mul_f32 v[10:11], v[2:3], v[68:69] op_sel_hi:[0,1]
	ds_read_b128 v[20:23], v6 offset:32256
	v_pk_fma_f32 v[14:15], v[2:3], v[72:73], v[106:107] op_sel_hi:[0,1,1]
	v_pk_fma_f32 v[10:11], v[2:3], v[70:71], v[10:11] op_sel:[1,0,0] op_sel_hi:[1,1,1]
	ds_read_b128 v[24:27], v6 offset:32512
	v_pk_fma_f32 v[14:15], v[2:3], v[74:75], v[14:15] op_sel:[1,0,0] op_sel_hi:[1,1,1]
	v_pk_fma_f32 v[10:11], v[4:5], v[76:77], v[10:11] op_sel_hi:[0,1,1]
	v_pk_fma_f32 v[14:15], v[4:5], v[80:81], v[14:15] op_sel_hi:[0,1,1]
	ds_read_b128 v[56:59], v7 offset:3584
	v_pk_fma_f32 v[10:11], v[4:5], v[78:79], v[10:11] op_sel:[1,0,0] op_sel_hi:[1,1,1]
	s_waitcnt lgkmcnt(7)
	v_pk_mul_f32 v[114:115], v[2:3], v[84:85]
	ds_read_b128 v[28:31], v6 offset:32768
	v_pk_mul_f32 v[116:117], v[4:5], v[86:87]
	v_add_f32_dpp v10, v10, v10 row_ror:8 row_mask:0xf bank_mask:0xf bound_ctrl:1
	v_add_f32_dpp v11, v11, v11 row_ror:8 row_mask:0xf bank_mask:0xf bound_ctrl:1
	ds_read_b128 v[32:35], v6 offset:33024
	v_pk_fma_f32 v[14:15], v[4:5], v[82:83], v[14:15] op_sel:[1,0,0] op_sel_hi:[1,1,1]
	v_add_f32_dpp v10, v10, v10 row_ror:4 row_mask:0xf bank_mask:0xf bound_ctrl:1
	ds_read_b128 v[36:39], v6 offset:33280
	v_add_f32_dpp v11, v11, v11 row_ror:4 row_mask:0xf bank_mask:0xf bound_ctrl:1
	v_pk_fma_f32 v[114:115], v[88:89], v[104:105], v[114:115] op_sel_hi:[1,0,1]
	v_add_f32_dpp v10, v10, v10 row_ror:2 row_mask:0xf bank_mask:0xf bound_ctrl:1
	ds_read_b128 v[40:43], v6 offset:33536
	v_add_f32_dpp v11, v11, v11 row_ror:2 row_mask:0xf bank_mask:0xf bound_ctrl:1
	v_pk_fma_f32 v[116:117], v[90:91], v[104:105], v[116:117] op_sel_hi:[1,0,1]
	ds_read_b128 v[48:51], v6 offset:34048
	v_add_f32_dpp v10, v10, v10 row_ror:1 row_mask:0xf bank_mask:0xf bound_ctrl:1
	v_add_f32_dpp v11, v11, v11 row_ror:1 row_mask:0xf bank_mask:0xf bound_ctrl:1
	s_waitcnt lgkmcnt(9)
	v_pk_fma_f32 v[114:115], v[96:97], v[104:105], v[114:115] op_sel:[0,1,0] op_sel_hi:[1,1,1]
	ds_read_b128 v[44:47], v6 offset:33792
	v_pk_fma_f32 v[116:117], v[98:99], v[104:105], v[116:117] op_sel:[0,1,0] op_sel_hi:[1,1,1]
	v_pk_fma_f32 v[114:115], v[92:93], v[10:11], v[114:115] op_sel_hi:[1,0,1] neg_lo:[1,0,0] neg_hi:[1,0,0]
	ds_read_b128 v[52:55], v6 offset:34304
	v_pk_fma_f32 v[116:117], v[94:95], v[10:11], v[116:117] op_sel_hi:[1,0,1] neg_lo:[1,0,0] neg_hi:[1,0,0]
	v_pk_fma_f32 v[2:3], v[100:101], v[10:11], v[114:115] op_sel:[0,1,0] op_sel_hi:[1,1,1] neg_lo:[1,0,0] neg_hi:[1,0,0]
	v_pk_fma_f32 v[4:5], v[102:103], v[10:11], v[116:117] op_sel:[0,1,0] op_sel_hi:[1,1,1] neg_lo:[1,0,0] neg_hi:[1,0,0]
	ds_write2st64_b32 v9, v14, v15 offset0:104 offset1:108
	s_waitcnt lgkmcnt(6)
	v_pk_mul_f32 v[10:11], v[2:3], v[20:21] op_sel_hi:[0,1]
	ds_read_b128 v[68:71], v6 offset:34560
	v_pk_fma_f32 v[14:15], v[2:3], v[24:25], v[58:59] op_sel_hi:[0,1,1]
	v_pk_fma_f32 v[10:11], v[2:3], v[22:23], v[10:11] op_sel:[1,0,0] op_sel_hi:[1,1,1]
	ds_read_b128 v[72:75], v6 offset:34816
	v_pk_fma_f32 v[14:15], v[2:3], v[26:27], v[14:15] op_sel:[1,0,0] op_sel_hi:[1,1,1]
	v_pk_fma_f32 v[10:11], v[4:5], v[28:29], v[10:11] op_sel_hi:[0,1,1]
	v_pk_fma_f32 v[14:15], v[4:5], v[32:33], v[14:15] op_sel_hi:[0,1,1]
	ds_read_b128 v[104:107], v7 offset:3840
	v_pk_fma_f32 v[10:11], v[4:5], v[30:31], v[10:11] op_sel:[1,0,0] op_sel_hi:[1,1,1]
	s_waitcnt lgkmcnt(7)
	v_pk_mul_f32 v[114:115], v[2:3], v[36:37]
	ds_read_b128 v[76:79], v6 offset:35072
	v_pk_mul_f32 v[116:117], v[4:5], v[38:39]
	v_add_f32_dpp v10, v10, v10 row_ror:8 row_mask:0xf bank_mask:0xf bound_ctrl:1
	v_add_f32_dpp v11, v11, v11 row_ror:8 row_mask:0xf bank_mask:0xf bound_ctrl:1
	ds_read_b128 v[80:83], v6 offset:35328
	v_pk_fma_f32 v[14:15], v[4:5], v[34:35], v[14:15] op_sel:[1,0,0] op_sel_hi:[1,1,1]
	v_add_f32_dpp v10, v10, v10 row_ror:4 row_mask:0xf bank_mask:0xf bound_ctrl:1
	ds_read_b128 v[84:87], v6 offset:35584
	v_add_f32_dpp v11, v11, v11 row_ror:4 row_mask:0xf bank_mask:0xf bound_ctrl:1
	v_pk_fma_f32 v[114:115], v[40:41], v[56:57], v[114:115] op_sel_hi:[1,0,1]
	v_add_f32_dpp v10, v10, v10 row_ror:2 row_mask:0xf bank_mask:0xf bound_ctrl:1
	ds_read_b128 v[88:91], v6 offset:35840
	v_add_f32_dpp v11, v11, v11 row_ror:2 row_mask:0xf bank_mask:0xf bound_ctrl:1
	v_pk_fma_f32 v[116:117], v[42:43], v[56:57], v[116:117] op_sel_hi:[1,0,1]
	ds_read_b128 v[96:99], v6 offset:36352
	v_add_f32_dpp v10, v10, v10 row_ror:1 row_mask:0xf bank_mask:0xf bound_ctrl:1
	v_add_f32_dpp v11, v11, v11 row_ror:1 row_mask:0xf bank_mask:0xf bound_ctrl:1
	s_waitcnt lgkmcnt(9)
	v_pk_fma_f32 v[114:115], v[48:49], v[56:57], v[114:115] op_sel:[0,1,0] op_sel_hi:[1,1,1]
	ds_read_b128 v[92:95], v6 offset:36096
	v_pk_fma_f32 v[116:117], v[50:51], v[56:57], v[116:117] op_sel:[0,1,0] op_sel_hi:[1,1,1]
	v_pk_fma_f32 v[114:115], v[44:45], v[10:11], v[114:115] op_sel_hi:[1,0,1] neg_lo:[1,0,0] neg_hi:[1,0,0]
	ds_read_b128 v[100:103], v6 offset:36608
	v_pk_fma_f32 v[116:117], v[46:47], v[10:11], v[116:117] op_sel_hi:[1,0,1] neg_lo:[1,0,0] neg_hi:[1,0,0]
	v_pk_fma_f32 v[2:3], v[52:53], v[10:11], v[114:115] op_sel:[0,1,0] op_sel_hi:[1,1,1] neg_lo:[1,0,0] neg_hi:[1,0,0]
	v_pk_fma_f32 v[4:5], v[54:55], v[10:11], v[116:117] op_sel:[0,1,0] op_sel_hi:[1,1,1] neg_lo:[1,0,0] neg_hi:[1,0,0]
	ds_write2st64_b32 v9, v14, v15 offset0:112 offset1:116
	s_waitcnt lgkmcnt(6)
	v_pk_mul_f32 v[10:11], v[2:3], v[68:69] op_sel_hi:[0,1]
	v_pk_fma_f32 v[14:15], v[2:3], v[72:73], v[106:107] op_sel_hi:[0,1,1]
	v_pk_fma_f32 v[10:11], v[2:3], v[70:71], v[10:11] op_sel:[1,0,0] op_sel_hi:[1,1,1]
	v_pk_fma_f32 v[14:15], v[2:3], v[74:75], v[14:15] op_sel:[1,0,0] op_sel_hi:[1,1,1]
	v_pk_fma_f32 v[10:11], v[4:5], v[76:77], v[10:11] op_sel_hi:[0,1,1]
	v_pk_fma_f32 v[14:15], v[4:5], v[80:81], v[14:15] op_sel_hi:[0,1,1]
	v_pk_fma_f32 v[10:11], v[4:5], v[78:79], v[10:11] op_sel:[1,0,0] op_sel_hi:[1,1,1]
	s_waitcnt lgkmcnt(4)
	v_pk_mul_f32 v[114:115], v[2:3], v[84:85]
	v_pk_mul_f32 v[116:117], v[4:5], v[86:87]
	v_add_f32_dpp v10, v10, v10 row_ror:8 row_mask:0xf bank_mask:0xf bound_ctrl:1
	v_add_f32_dpp v11, v11, v11 row_ror:8 row_mask:0xf bank_mask:0xf bound_ctrl:1
	v_pk_fma_f32 v[14:15], v[4:5], v[82:83], v[14:15] op_sel:[1,0,0] op_sel_hi:[1,1,1]
	v_add_f32_dpp v10, v10, v10 row_ror:4 row_mask:0xf bank_mask:0xf bound_ctrl:1
	v_add_f32_dpp v11, v11, v11 row_ror:4 row_mask:0xf bank_mask:0xf bound_ctrl:1
	v_pk_fma_f32 v[114:115], v[88:89], v[104:105], v[114:115] op_sel_hi:[1,0,1]
	v_add_f32_dpp v10, v10, v10 row_ror:2 row_mask:0xf bank_mask:0xf bound_ctrl:1
	v_add_f32_dpp v11, v11, v11 row_ror:2 row_mask:0xf bank_mask:0xf bound_ctrl:1
	v_pk_fma_f32 v[116:117], v[90:91], v[104:105], v[116:117] op_sel_hi:[1,0,1]
	v_add_f32_dpp v10, v10, v10 row_ror:1 row_mask:0xf bank_mask:0xf bound_ctrl:1
	v_add_f32_dpp v11, v11, v11 row_ror:1 row_mask:0xf bank_mask:0xf bound_ctrl:1
	s_waitcnt lgkmcnt(1)
	v_pk_fma_f32 v[114:115], v[96:97], v[104:105], v[114:115] op_sel:[0,1,0] op_sel_hi:[1,1,1]
	v_pk_fma_f32 v[116:117], v[98:99], v[104:105], v[116:117] op_sel:[0,1,0] op_sel_hi:[1,1,1]
	v_pk_fma_f32 v[114:115], v[92:93], v[10:11], v[114:115] op_sel_hi:[1,0,1] neg_lo:[1,0,0] neg_hi:[1,0,0]
	v_pk_fma_f32 v[116:117], v[94:95], v[10:11], v[116:117] op_sel_hi:[1,0,1] neg_lo:[1,0,0] neg_hi:[1,0,0]
	v_pk_fma_f32 v[2:3], v[100:101], v[10:11], v[114:115] op_sel:[0,1,0] op_sel_hi:[1,1,1] neg_lo:[1,0,0] neg_hi:[1,0,0]
	v_pk_fma_f32 v[4:5], v[102:103], v[10:11], v[116:117] op_sel:[0,1,0] op_sel_hi:[1,1,1] neg_lo:[1,0,0] neg_hi:[1,0,0]
	ds_write2st64_b32 v9, v14, v15 offset0:120 offset1:124
	v_add_u32_e32 v6, s1, v6
	v_add_u32_e32 v7, vcc_lo, v7
	v_add_u32_e32 v9, s1, v9
	s_sub_i32 s1, 0, s1
	s_sub_i32 vcc_lo, 0, vcc_lo
	s_add_i32 s0, s0, 1
	ds_read_b128 v[120:123], v17
	s_waitcnt lgkmcnt(0)
	v_mov_b32_e32 v18, s0
	s_mov_b64 exec, 1
	ds_write_b32 v16, v18
	s_mov_b64 exec, -1
	s_cmpk_eq_i32 s0, 0x200
	s_cbranch_scc1 .Lscan_done
	v_min_u32_e32 v120, v120, v121
	v_min_u32_e32 v122, v122, v123
	v_min_u32_e32 v120, v120, v122
	s_nop 0
	v_readfirstlane_b32 vcc_hi, v120
	s_nop 3
	s_cmp_gt_u32 vcc_hi, s0
	s_cbranch_scc1 .LBB0_652
.Lscan_wait:
	s_sleep 1
	ds_read_b128 v[120:123], v17
	s_waitcnt lgkmcnt(0)
	v_min_u32_e32 v120, v120, v121
	v_min_u32_e32 v122, v122, v123
	v_min_u32_e32 v120, v120, v122
	s_nop 0
	v_readfirstlane_b32 vcc_hi, v120
	s_nop 3
	s_cmp_gt_u32 vcc_hi, s0
	s_cbranch_scc0 .Lscan_wait
	s_branch .LBB0_652

.LBB0_654:
	s_and_b64 vcc, exec, s[0:1]
	s_cbranch_vccz .LBB0_676
	s_lshl_b32 s60, s50, 2
	s_add_i32 s60, s60, 0x255f0
	v_mov_b32_e32 v224, s60
	v_mov_b32_e32 v225, 0x25610
	v_bfe_u32 v214, v153, 4, 4
	v_and_b32_e32 v215, 15, v153
	v_mul_u32_u24_e32 v216, 48, v214
	v_add_u32_e32 v217, 0x11b00, v216
	v_mul_u32_u24_e32 v218, 0x900, v214
	v_lshl_add_u32 v218, v215, 4, v218
	v_add_u32_e32 v219, 0x11b00, v218
	v_lshlrev_b32_e32 v220, 7, v214
	v_lshl_add_u32 v220, v215, 2, v220
	v_add_u32_e32 v220, 0x9300, v220
	v_add_u32_e32 v221, 0x11b00, v220
	v_lshlrev_b32_e32 v222, 8, v214
	v_lshl_add_u32 v222, v215, 4, v222
	v_add_u32_e32 v222, 0x23600, v222
	v_add_u32_e32 v223, 0x1000, v222
	s_lshl_b32 s0, s2, 8
	s_and_b32 s4, s0, 0x4000
	s_add_u32 s12, s70, 0x4000000
	s_addc_u32 s13, s71, 0
	s_add_u32 s14, s70, 0x8000000
	s_addc_u32 s15, s71, 0
	s_add_u32 s20, s70, 0xc000000
	s_addc_u32 s21, s71, 0
	s_add_u32 s16, s78, 0x30000000
	s_addc_u32 s17, s79, 0
	s_add_u32 s18, s78, 0x34000000
	s_addc_u32 s19, s79, 0
	s_and_b32 s0, s2, 0x60
	s_lshl_b32 s24, s2, 2
	s_bfe_u32 s6, s2, 0x20003
	v_add_u32_e32 v20, 0xffffff00, v153
	s_and_b32 s1, s24, 28
	s_or_b32 s0, s6, s0
	v_ashrrev_i32_e32 v1, 4, v20
	s_or_b32 s25, s0, s1
	v_lshlrev_b32_e32 v26, 1, v1
	s_mov_b32 s5, 0
	s_lshl_b32 s0, s25, 4
	v_and_b32_e32 v23, 15, v153
	v_ashrrev_i32_e32 v27, 31, v26
	s_and_b32 s1, s0, 0x3c0
	v_lshlrev_b32_e32 v22, 2, v23
	v_lshl_add_u64 v[2:3], v[26:27], 0, s[4:5]
	v_or_b32_e32 v55, s1, v22
	v_lshlrev_b64 v[28:29], 10, v[2:3]
	v_or_b32_e32 v2, v28, v55
	v_mov_b32_e32 v3, v29
	v_lshlrev_b64 v[6:7], 1, v[2:3]
	v_lshl_add_u64 v[4:5], s[16:17], 0, v[6:7]
	v_lshl_add_u64 v[2:3], s[70:71], 0, v[6:7]
	global_load_dwordx2 v[8:9], v[4:5], off
	v_lshl_add_u64 v[4:5], s[12:13], 0, v[6:7]
	global_load_dwordx2 v[10:11], v[4:5], off
	v_lshl_add_u64 v[4:5], s[14:15], 0, v[6:7]
	global_load_dwordx2 v[12:13], v[2:3], off
	global_load_dwordx2 v[24:25], v[4:5], off
	global_load_dwordx2 v[14:15], v[2:3], off offset:2048
	v_lshl_add_u64 v[2:3], s[18:19], 0, v[6:7]
	v_or_b32_e32 v6, 0x800, v6
	v_lshl_add_u64 v[4:5], s[12:13], 0, v[6:7]
	global_load_dwordx2 v[16:17], v[4:5], off
	v_lshl_add_u64 v[4:5], s[16:17], 0, v[6:7]
	global_load_dwordx2 v[18:19], v[4:5], off
	global_load_dwordx2 v[38:39], v[2:3], off
	v_ashrrev_i32_e32 v4, 3, v20
	v_ashrrev_i32_e32 v5, 31, v4
	v_lshl_add_u64 v[30:31], s[4:5], 0, v[4:5]
	v_lshlrev_b64 v[32:33], 11, v[30:31]
	v_lshlrev_b32_e32 v2, 1, v153
	s_mov_b32 s7, s5
	v_lshl_add_u64 v[20:21], s[20:21], 0, v[32:33]
	s_and_b32 s0, s0, 48
	s_lshl_b32 s6, s1, 1
	s_mov_b32 s9, s5
	v_and_b32_e32 v58, 14, v2
	s_lshl_b32 s8, s0, 1
	v_lshl_add_u64 v[20:21], v[20:21], 0, s[6:7]
	v_mov_b32_e32 v3, 0
	v_lshlrev_b32_e32 v2, 1, v58
	v_lshl_add_u64 v[20:21], v[20:21], 0, s[8:9]
	v_lshl_add_u64 v[20:21], v[20:21], 0, v[2:3]
	v_lshl_add_u64 v[34:35], s[14:15], 0, v[6:7]
	v_lshl_add_u64 v[6:7], s[18:19], 0, v[6:7]
	global_load_dword v3, v[20:21], off
	global_load_dwordx2 v[40:41], v[34:35], off
	global_load_dwordx2 v[42:43], v[6:7], off
	v_lshl_add_u32 v59, v23, 4, 0
	s_movk_i32 s0, 0x900
	v_mad_i32_i24 v54, v1, s0, v59
	v_cmp_eq_u32_e64 s[0:1], 0, v23
	v_cmp_ne_u32_e32 vcc, 0, v23
	v_mul_i32_i24_e32 v23, 48, v1
	s_waitcnt vmcnt(0)
	v_cvt_f32_f16_e32 v6, v8
	v_cvt_f32_f16_sdwa v7, v8 dst_sel:DWORD dst_unused:UNUSED_PAD src0_sel:WORD_1
	v_cvt_f32_f16_e32 v20, v10
	v_cvt_f32_f16_sdwa v21, v10 dst_sel:DWORD dst_unused:UNUSED_PAD src0_sel:WORD_1
	v_cvt_f32_f16_e32 v44, v12
	v_cvt_f32_f16_sdwa v45, v12 dst_sel:DWORD dst_unused:UNUSED_PAD src0_sel:WORD_1
	v_cvt_f32_f16_e32 v46, v14
	v_cvt_f32_f16_sdwa v47, v14 dst_sel:DWORD dst_unused:UNUSED_PAD src0_sel:WORD_1
	v_cvt_f32_f16_e32 v10, v11
	v_cvt_f32_f16_sdwa v11, v11 dst_sel:DWORD dst_unused:UNUSED_PAD src0_sel:WORD_1
	v_cvt_f32_f16_e32 v48, v13
	v_cvt_f32_f16_sdwa v49, v13 dst_sel:DWORD dst_unused:UNUSED_PAD src0_sel:WORD_1
	v_cvt_f32_f16_e32 v50, v15
	v_cvt_f32_f16_sdwa v51, v15 dst_sel:DWORD dst_unused:UNUSED_PAD src0_sel:WORD_1
	v_cvt_f32_f16_e32 v12, v16
	v_cvt_f32_f16_sdwa v13, v16 dst_sel:DWORD dst_unused:UNUSED_PAD src0_sel:WORD_1
	v_cvt_f32_f16_e32 v14, v17
	v_cvt_f32_f16_sdwa v15, v17 dst_sel:DWORD dst_unused:UNUSED_PAD src0_sel:WORD_1
	v_cvt_f32_f16_e32 v52, v18
	v_cvt_f32_f16_sdwa v53, v18 dst_sel:DWORD dst_unused:UNUSED_PAD src0_sel:WORD_1
	v_cvt_f32_f16_e32 v56, v19
	v_cvt_f32_f16_sdwa v57, v19 dst_sel:DWORD dst_unused:UNUSED_PAD src0_sel:WORD_1
	v_cvt_f32_f16_e32 v8, v9
	v_cvt_f32_f16_sdwa v9, v9 dst_sel:DWORD dst_unused:UNUSED_PAD src0_sel:WORD_1
	v_pk_add_f32 v[20:21], v[20:21], 1.0 op_sel_hi:[1,0] neg_lo:[1,0] neg_hi:[1,0]
	v_pk_add_f32 v[60:61], v[10:11], 1.0 op_sel_hi:[1,0] neg_lo:[1,0] neg_hi:[1,0]
	v_pk_add_f32 v[62:63], v[12:13], 1.0 op_sel_hi:[1,0] neg_lo:[1,0] neg_hi:[1,0]
	v_pk_add_f32 v[64:65], v[14:15], 1.0 op_sel_hi:[1,0] neg_lo:[1,0] neg_hi:[1,0]
	v_pk_mul_f32 v[14:15], v[20:21], v[52:53]
	v_pk_mul_f32 v[16:17], v[60:61], v[56:57]
	v_pk_mul_f32 v[66:67], v[62:63], v[46:47]
	v_pk_mul_f32 v[68:69], v[64:65], v[50:51]
	v_pk_mul_f32 v[10:11], v[20:21], v[44:45]
	v_pk_mul_f32 v[12:13], v[60:61], v[48:49]
	v_pk_mul_f32 v[18:19], v[20:21], v[62:63]
	v_pk_mul_f32 v[34:35], v[20:21], v[66:67]
	v_pk_mul_f32 v[36:37], v[60:61], v[68:69]
	v_pk_mul_f32 v[20:21], v[60:61], v[64:65]
	v_mov_b32_e32 v120, v6
	v_mov_b32_e32 v121, v14
	v_mov_b32_e32 v122, v7
	v_mov_b32_e32 v123, v15
	v_mov_b32_e32 v124, v10
	v_mov_b32_e32 v125, v34
	v_mov_b32_e32 v126, v11
	v_mov_b32_e32 v127, v35
	v_mov_b32_e32 v128, v8
	v_mov_b32_e32 v129, v16
	v_mov_b32_e32 v130, v9
	v_mov_b32_e32 v131, v17
	v_mov_b32_e32 v132, v12
	v_mov_b32_e32 v133, v36
	v_mov_b32_e32 v134, v13
	v_mov_b32_e32 v135, v37
	ds_write_b128 v54, v[18:21] offset:1024
	v_cvt_f32_f16_e32 v14, v38
	v_cvt_f32_f16_sdwa v16, v38 dst_sel:DWORD dst_unused:UNUSED_PAD src0_sel:WORD_1
	v_cvt_f32_f16_e32 v15, v24
	v_cvt_f32_f16_sdwa v17, v24 dst_sel:DWORD dst_unused:UNUSED_PAD src0_sel:WORD_1
	v_cvt_f32_f16_e32 v21, v25
	v_cvt_f32_f16_sdwa v25, v25 dst_sel:DWORD dst_unused:UNUSED_PAD src0_sel:WORD_1
	v_cvt_f32_f16_e32 v20, v39
	v_cvt_f32_f16_sdwa v24, v39 dst_sel:DWORD dst_unused:UNUSED_PAD src0_sel:WORD_1
	v_mov_b32_e32 v8, v14
	v_mov_b32_e32 v9, v16
	v_mov_b32_e32 v6, v15
	v_mov_b32_e32 v7, v17
	v_pk_mul_f32 v[10:11], v[62:63], v[8:9]
	v_mov_b32_e32 v8, v21
	v_mov_b32_e32 v9, v25
	v_pk_mul_f32 v[6:7], v[62:63], v[6:7]
	v_pk_mul_f32 v[8:9], v[64:65], v[8:9]
	v_mov_b32_e32 v12, v20
	v_mov_b32_e32 v13, v24
	v_mov_b32_e32 v18, v53
	v_pk_mul_f32 v[12:13], v[64:65], v[12:13]
	v_mov_b32_e32 v182, v6
	v_mov_b32_e32 v183, v7
	v_mov_b32_e32 v184, v8
	v_mov_b32_e32 v185, v9
	ds_write_b128 v54, v[10:13] offset:1536
	v_pk_fma_f32 v[6:7], v[52:53], v[14:15], 0 op_sel_hi:[0,1,0]
	v_pk_fma_f32 v[6:7], v[18:19], v[16:17], v[6:7] op_sel_hi:[0,1,1]
	v_mov_b32_e32 v10, v45
	v_pk_fma_f32 v[18:19], v[44:45], v[14:15], 0 op_sel_hi:[0,1,0]
	v_pk_fma_f32 v[14:15], v[66:67], v[14:15], 0 op_sel_hi:[0,1,0]
	v_pk_fma_f32 v[10:11], v[10:11], v[16:17], v[18:19] op_sel_hi:[0,1,1]
	v_pk_fma_f32 v[14:15], v[66:67], v[16:17], v[14:15] op_sel:[1,0,0]
	v_mov_b32_e32 v34, v57
	v_pk_fma_f32 v[6:7], v[56:57], v[20:21], v[6:7] op_sel_hi:[0,1,1]
	v_mov_b32_e32 v12, v49
	v_pk_fma_f32 v[10:11], v[48:49], v[20:21], v[10:11] op_sel_hi:[0,1,1]
	v_pk_fma_f32 v[14:15], v[68:69], v[20:21], v[14:15] op_sel_hi:[0,1,1]
	v_pk_fma_f32 v[6:7], v[34:35], v[24:25], v[6:7] op_sel_hi:[0,1,1]
	v_pk_fma_f32 v[10:11], v[12:13], v[24:25], v[10:11] op_sel_hi:[0,1,1]
	v_pk_fma_f32 v[14:15], v[68:69], v[24:25], v[14:15] op_sel:[1,0,0]
	v_cvt_f32_f16_e32 v25, v40
	v_cvt_f32_f16_sdwa v35, v40 dst_sel:DWORD dst_unused:UNUSED_PAD src0_sel:WORD_1
	v_cvt_f32_f16_e32 v39, v41
	v_cvt_f32_f16_sdwa v41, v41 dst_sel:DWORD dst_unused:UNUSED_PAD src0_sel:WORD_1
	v_cvt_f32_f16_e32 v24, v42
	v_cvt_f32_f16_sdwa v34, v42 dst_sel:DWORD dst_unused:UNUSED_PAD src0_sel:WORD_1
	v_cvt_f32_f16_e32 v38, v43
	v_cvt_f32_f16_sdwa v40, v43 dst_sel:DWORD dst_unused:UNUSED_PAD src0_sel:WORD_1
	v_mov_b32_e32 v18, v25
	v_mov_b32_e32 v19, v35
	v_mov_b32_e32 v20, v39
	v_mov_b32_e32 v21, v41
	ds_write_b128 v54, v[18:21] offset:1792
	v_mov_b32_e32 v18, v24
	v_mov_b32_e32 v19, v34
	v_mov_b32_e32 v20, v38
	v_mov_b32_e32 v21, v40
	v_mov_b32_e32 v36, v47
	ds_write_b128 v54, v[18:21] offset:2048
	v_mov_b32_e32 v186, v18
	v_mov_b32_e32 v187, v19
	v_mov_b32_e32 v188, v20
	v_mov_b32_e32 v189, v21
	v_pk_fma_f32 v[18:19], v[46:47], v[24:25], 0 op_sel_hi:[0,1,0]
	v_pk_fma_f32 v[18:19], v[36:37], v[34:35], v[18:19] op_sel_hi:[0,1,1]
	v_mov_b32_e32 v42, v51
	v_pk_fma_f32 v[18:19], v[50:51], v[38:39], v[18:19] op_sel_hi:[0,1,1]
	v_pk_fma_f32 v[18:19], v[42:43], v[40:41], v[18:19] op_sel_hi:[0,1,1]
	v_mov_b32_dpp v8, v6 row_ror:8 row_mask:0xf bank_mask:0xf bound_ctrl:1
	v_mov_b32_dpp v9, v7 row_ror:8 row_mask:0xf bank_mask:0xf bound_ctrl:1
	v_mov_b32_dpp v12, v10 row_ror:8 row_mask:0xf bank_mask:0xf bound_ctrl:1
	v_mov_b32_dpp v13, v11 row_ror:8 row_mask:0xf bank_mask:0xf bound_ctrl:1
	v_mov_b32_dpp v16, v14 row_ror:8 row_mask:0xf bank_mask:0xf bound_ctrl:1
	v_mov_b32_dpp v17, v15 row_ror:8 row_mask:0xf bank_mask:0xf bound_ctrl:1
	v_mov_b32_dpp v20, v18 row_ror:8 row_mask:0xf bank_mask:0xf bound_ctrl:1
	v_mov_b32_dpp v21, v19 row_ror:8 row_mask:0xf bank_mask:0xf bound_ctrl:1
	v_pk_add_f32 v[6:7], v[6:7], v[8:9]
	v_pk_add_f32 v[10:11], v[10:11], v[12:13]
	v_pk_add_f32 v[14:15], v[14:15], v[16:17]
	v_pk_add_f32 v[18:19], v[18:19], v[20:21]
	v_mov_b32_dpp v8, v6 row_ror:4 row_mask:0xf bank_mask:0xf bound_ctrl:1
	v_mov_b32_dpp v9, v7 row_ror:4 row_mask:0xf bank_mask:0xf bound_ctrl:1
	v_mov_b32_dpp v12, v10 row_ror:4 row_mask:0xf bank_mask:0xf bound_ctrl:1
	v_mov_b32_dpp v13, v11 row_ror:4 row_mask:0xf bank_mask:0xf bound_ctrl:1
	v_mov_b32_dpp v16, v14 row_ror:4 row_mask:0xf bank_mask:0xf bound_ctrl:1
	v_mov_b32_dpp v17, v15 row_ror:4 row_mask:0xf bank_mask:0xf bound_ctrl:1
	v_mov_b32_dpp v20, v18 row_ror:4 row_mask:0xf bank_mask:0xf bound_ctrl:1
	v_mov_b32_dpp v21, v19 row_ror:4 row_mask:0xf bank_mask:0xf bound_ctrl:1
	v_pk_add_f32 v[6:7], v[6:7], v[8:9]
	v_pk_add_f32 v[10:11], v[10:11], v[12:13]
	v_pk_add_f32 v[14:15], v[14:15], v[16:17]
	v_pk_add_f32 v[18:19], v[18:19], v[20:21]
	v_mov_b32_dpp v8, v6 row_ror:2 row_mask:0xf bank_mask:0xf bound_ctrl:1
	v_mov_b32_dpp v9, v7 row_ror:2 row_mask:0xf bank_mask:0xf bound_ctrl:1
	v_mov_b32_dpp v12, v10 row_ror:2 row_mask:0xf bank_mask:0xf bound_ctrl:1
	v_mov_b32_dpp v13, v11 row_ror:2 row_mask:0xf bank_mask:0xf bound_ctrl:1
	v_mov_b32_dpp v16, v14 row_ror:2 row_mask:0xf bank_mask:0xf bound_ctrl:1
	v_mov_b32_dpp v17, v15 row_ror:2 row_mask:0xf bank_mask:0xf bound_ctrl:1
	v_mov_b32_dpp v20, v18 row_ror:2 row_mask:0xf bank_mask:0xf bound_ctrl:1
	v_mov_b32_dpp v21, v19 row_ror:2 row_mask:0xf bank_mask:0xf bound_ctrl:1
	v_pk_add_f32 v[6:7], v[6:7], v[8:9]
	v_pk_add_f32 v[10:11], v[10:11], v[12:13]
	v_pk_add_f32 v[14:15], v[14:15], v[16:17]
	v_pk_add_f32 v[18:19], v[18:19], v[20:21]
	v_mov_b32_dpp v8, v6 row_ror:1 row_mask:0xf bank_mask:0xf bound_ctrl:1
	v_mov_b32_dpp v9, v7 row_ror:1 row_mask:0xf bank_mask:0xf bound_ctrl:1
	v_mov_b32_dpp v12, v10 row_ror:1 row_mask:0xf bank_mask:0xf bound_ctrl:1
	v_mov_b32_dpp v13, v11 row_ror:1 row_mask:0xf bank_mask:0xf bound_ctrl:1
	v_mov_b32_dpp v16, v14 row_ror:1 row_mask:0xf bank_mask:0xf bound_ctrl:1
	v_mov_b32_dpp v17, v15 row_ror:1 row_mask:0xf bank_mask:0xf bound_ctrl:1
	v_mov_b32_dpp v20, v18 row_ror:1 row_mask:0xf bank_mask:0xf bound_ctrl:1
	v_mov_b32_dpp v21, v19 row_ror:1 row_mask:0xf bank_mask:0xf bound_ctrl:1
	s_and_saveexec_b64 s[10:11], vcc
	s_xor_b64 s[10:11], exec, s[10:11]
	v_mul_i32_i24_e32 v23, 48, v1
	s_or_saveexec_b64 s[10:11], s[10:11]
	v_mul_i32_i24_e32 v62, 0x900, v1
	s_xor_b64 exec, exec, s[10:11]
	s_cbranch_execz .LBB0_659
	v_pk_add_f32 v[6:7], v[6:7], v[8:9]
	v_pk_add_f32 v[8:9], v[10:11], v[12:13]
	s_mov_b32 s22, 0x3d800000
	v_pk_mul_f32 v[8:9], v[8:9], s[22:23] op_sel_hi:[1,0]
	v_mad_i32_i24 v1, v1, 48, 0
	ds_write_b128 v1, v[6:9] offset:36864
	v_pk_add_f32 v[6:7], v[14:15], v[16:17]
	v_pk_add_f32 v[8:9], v[18:19], v[20:21]
	v_pk_mul_f32 v[6:7], v[6:7], s[22:23] op_sel_hi:[1,0]
	v_pk_mul_f32 v[8:9], v[8:9], s[22:23] op_sel_hi:[1,0]
	ds_write_b128 v1, v[6:9] offset:36880
.LBB0_659:
	s_or_b64 exec, exec, s[10:11]
	s_or_b32 s22, s4, 32
	s_mov_b32 s23, s5
	v_lshl_add_u64 v[6:7], s[22:23], 0, v[26:27]
	v_lshlrev_b64 v[6:7], 11, v[6:7]
	v_lshlrev_b32_e32 v25, 1, v55
	v_or_b32_e32 v6, v6, v25
	v_lshl_add_u64 v[8:9], s[70:71], 0, v[6:7]
	v_lshl_add_u64 v[10:11], s[12:13], 0, v[6:7]
	v_lshl_add_u64 v[12:13], s[14:15], 0, v[6:7]
	v_lshl_add_u64 v[14:15], s[16:17], 0, v[6:7]
	v_lshl_add_u64 v[16:17], s[18:19], 0, v[6:7]
	v_or_b32_e32 v6, 0x800, v6
	global_load_dwordx2 v[10:11], v[10:11], off
	v_lshl_add_u64 v[18:19], s[12:13], 0, v[6:7]
	global_load_dwordx2 v[14:15], v[14:15], off
	s_nop 0
	global_load_dwordx2 v[18:19], v[18:19], off
	s_nop 0
	global_load_dwordx2 v[20:21], v[8:9], off
	global_load_dwordx2 v[56:57], v[12:13], off
	s_nop 0
	global_load_dwordx2 v[12:13], v[8:9], off offset:2048
	v_lshl_add_u64 v[8:9], s[16:17], 0, v[6:7]
	global_load_dwordx2 v[64:65], v[8:9], off
	global_load_dwordx2 v[68:69], v[16:17], off
	v_cvt_f32_f16_sdwa v9, v3 dst_sel:DWORD dst_unused:UNUSED_PAD src0_sel:WORD_1
	v_cvt_f32_f16_e32 v8, v3
	s_or_b32 s26, s4, 64
	s_mov_b32 s27, s5
	v_lshl_add_u64 v[34:35], s[22:23], 0, v[4:5]
	v_lshl_add_u64 v[36:37], s[26:27], 0, v[26:27]
	v_lshlrev_b32_e32 v1, 6, v4
	s_mov_b32 s11, 0
	v_lshlrev_b32_e32 v24, 2, v58
	v_lshl_add_u64 v[38:39], s[26:27], 0, v[4:5]
	v_lshlrev_b64 v[34:35], 11, v[34:35]
	v_lshlrev_b64 v[36:37], 11, v[36:37]
	v_add3_u32 v1, 0, v1, v24
	s_mov_b32 s7, s11
	v_lshlrev_b64 v[38:39], 11, v[38:39]
	v_lshl_add_u64 v[34:35], s[20:21], 0, v[34:35]
	v_or_b32_e32 v36, v36, v25
	v_lshl_add_u64 v[38:39], s[20:21], 0, v[38:39]
	ds_write_b64 v1, v[8:9] offset:37632
	ds_read_b128 v[198:201], v216 offset:36864
	ds_read_b128 v[202:205], v216 offset:36880
	ds_read2_b32 v[206:207], v220 offset1:16
	s_waitcnt lgkmcnt(0)
	v_mul_f32_e32 v210, 0x41800000, v200
	v_mul_f32_e32 v211, 0x41800000, v202
	v_mul_f32_e32 v212, 0x41800000, v204
	v_fma_f32 v213, -v204, v199, v203
	v_fma_f32 v121, -v198, v120, v121
	v_fma_f32 v124, -v210, v120, v124
	v_fma_f32 v125, -v211, v120, v125
	v_fma_f32 v123, -v198, v122, v123
	v_fma_f32 v126, -v210, v122, v126
	v_fma_f32 v127, -v211, v122, v127
	v_fma_f32 v129, -v198, v128, v129
	v_fma_f32 v132, -v210, v128, v132
	v_fma_f32 v133, -v211, v128, v133
	v_fma_f32 v131, -v198, v130, v131
	v_fma_f32 v134, -v210, v130, v134
	v_fma_f32 v135, -v211, v130, v135
	v_fma_f32 v182, -v199, v186, v182
	v_fma_f32 v183, -v199, v187, v183
	v_fma_f32 v184, -v199, v188, v184
	v_fma_f32 v185, -v199, v189, v185
	v_fma_f32 v125, -v212, v121, v125
	v_fma_f32 v127, -v212, v123, v127
	v_fma_f32 v133, -v212, v129, v133
	v_fma_f32 v135, -v212, v131, v135
	v_mul_f32_e32 v208, v206, v201
	v_mul_f32_e32 v209, v206, v213
	ds_write_b128 v218, v[120:123]
	v_fmac_f32_e32 v209, v207, v205
	ds_write_b128 v218, v[124:127] offset:256
	ds_write_b128 v218, v[128:131] offset:512
	ds_write_b128 v218, v[132:135] offset:768
	ds_write_b128 v218, v[182:185] offset:1280
	ds_write_b128 v222, v[206:209]
	v_lshl_add_u64 v[8:9], v[34:35], 0, s[6:7]
	v_lshl_add_u64 v[34:35], s[14:15], 0, v[36:37]
	v_lshl_add_u64 v[40:41], s[16:17], 0, v[36:37]
	v_lshl_add_u64 v[50:51], s[14:15], 0, v[6:7]
	v_lshl_add_u64 v[46:47], s[18:19], 0, v[36:37]
	v_lshl_add_u64 v[48:49], v[38:39], 0, s[6:7]
	v_lshl_add_u64 v[6:7], s[18:19], 0, v[6:7]
	global_load_dwordx2 v[38:39], v[34:35], off
	global_load_dwordx2 v[42:43], v[40:41], off
	s_nop 0
	global_load_dwordx2 v[40:41], v[46:47], off
	global_load_dwordx2 v[70:71], v[50:51], off
	global_load_dwordx2 v[72:73], v[6:7], off
	s_add_i32 s10, 0, 0x11b00
	s_mov_b32 s9, s11
	v_lshl_add_u64 v[16:17], s[70:71], 0, v[36:37]
	v_lshl_add_u64 v[44:45], s[12:13], 0, v[36:37]
	v_or_b32_e32 v36, 0x800, v36
	v_mov_b32_e32 v3, 0
	v_lshl_add_u32 v22, v22, 2, s10
	v_lshl_add_u64 v[8:9], v[8:9], 0, s[8:9]
	v_lshl_add_u64 v[34:35], s[12:13], 0, v[36:37]
	v_lshl_add_u64 v[46:47], s[14:15], 0, v[36:37]
	v_lshl_add_u64 v[66:67], s[16:17], 0, v[36:37]
	v_lshl_add_u64 v[36:37], s[18:19], 0, v[36:37]
	v_lshl_add_u64 v[48:49], v[48:49], 0, s[8:9]
	v_add_u32_e32 v76, v22, v62
	v_lshl_add_u64 v[6:7], v[8:9], 0, v[2:3]
	global_load_dwordx2 v[52:53], v[34:35], off
	s_nop 0
	global_load_dwordx2 v[34:35], v[46:47], off
	s_nop 0
	global_load_dwordx2 v[46:47], v[66:67], off
	s_nop 0
	global_load_dwordx2 v[36:37], v[36:37], off
	v_lshl_add_u64 v[8:9], v[48:49], 0, v[2:3]
	global_load_dwordx2 v[50:51], v[44:45], off
	global_load_dword v22, v[6:7], off
	global_load_dwordx2 v[48:49], v[16:17], off
	s_nop 0
	global_load_dwordx2 v[44:45], v[16:17], off offset:2048
	global_load_dword v61, v[8:9], off
	s_waitcnt lgkmcnt(0)
	s_mov_b32 s61, 1
	s_waitcnt lgkmcnt(0)
	v_mov_b32_e32 v226, s61
	s_mov_b64 s[58:59], exec
	s_mov_b64 exec, 1
	ds_write_b32 v224, v226
	s_mov_b64 exec, s[58:59]
	s_waitcnt lgkmcnt(0)
	s_barrier
	v_lshlrev_b32_e32 v60, 4, v4
	v_add_u32_e32 v77, 0, v23
	s_waitcnt vmcnt(19)
	v_cvt_f32_f16_e32 v16, v18
	v_cvt_f32_f16_sdwa v17, v18 dst_sel:DWORD dst_unused:UNUSED_PAD src0_sel:WORD_1
	v_cvt_f32_f16_e32 v8, v10
	v_cvt_f32_f16_sdwa v9, v10 dst_sel:DWORD dst_unused:UNUSED_PAD src0_sel:WORD_1
	v_cvt_f32_f16_e32 v10, v11
	v_pk_add_f32 v[78:79], v[16:17], 1.0 op_sel_hi:[1,0] neg_lo:[1,0] neg_hi:[1,0]
	v_cvt_f32_f16_e32 v16, v19
	v_cvt_f32_f16_sdwa v17, v19 dst_sel:DWORD dst_unused:UNUSED_PAD src0_sel:WORD_1
	v_cvt_f32_f16_sdwa v11, v11 dst_sel:DWORD dst_unused:UNUSED_PAD src0_sel:WORD_1
	s_waitcnt vmcnt(16)
	v_cvt_f32_f16_e32 v80, v12
	v_cvt_f32_f16_sdwa v81, v12 dst_sel:DWORD dst_unused:UNUSED_PAD src0_sel:WORD_1
	s_waitcnt vmcnt(15)
	v_cvt_f32_f16_e32 v82, v64
	v_cvt_f32_f16_sdwa v83, v64 dst_sel:DWORD dst_unused:UNUSED_PAD src0_sel:WORD_1
	v_cvt_f32_f16_e32 v92, v65
	v_cvt_f32_f16_sdwa v93, v65 dst_sel:DWORD dst_unused:UNUSED_PAD src0_sel:WORD_1
	v_cvt_f32_f16_e32 v94, v13
	v_cvt_f32_f16_sdwa v95, v13 dst_sel:DWORD dst_unused:UNUSED_PAD src0_sel:WORD_1
	v_cvt_f32_f16_e32 v6, v14
	v_cvt_f32_f16_sdwa v7, v14 dst_sel:DWORD dst_unused:UNUSED_PAD src0_sel:WORD_1
	v_cvt_f32_f16_e32 v74, v20
	v_pk_add_f32 v[66:67], v[8:9], 1.0 op_sel_hi:[1,0] neg_lo:[1,0] neg_hi:[1,0]
	v_cvt_f32_f16_sdwa v75, v20 dst_sel:DWORD dst_unused:UNUSED_PAD src0_sel:WORD_1
	v_cvt_f32_f16_e32 v8, v15
	v_cvt_f32_f16_sdwa v9, v15 dst_sel:DWORD dst_unused:UNUSED_PAD src0_sel:WORD_1
	v_cvt_f32_f16_e32 v90, v21
	v_cvt_f32_f16_sdwa v91, v21 dst_sel:DWORD dst_unused:UNUSED_PAD src0_sel:WORD_1
	v_pk_add_f32 v[86:87], v[16:17], 1.0 op_sel_hi:[1,0] neg_lo:[1,0] neg_hi:[1,0]
	v_pk_add_f32 v[88:89], v[10:11], 1.0 op_sel_hi:[1,0] neg_lo:[1,0] neg_hi:[1,0]
	v_pk_mul_f32 v[84:85], v[78:79], v[80:81]
	v_pk_mul_f32 v[14:15], v[66:67], v[82:83]
	v_pk_mul_f32 v[16:17], v[88:89], v[92:93]
	v_pk_mul_f32 v[96:97], v[86:87], v[94:95]
	v_pk_mul_f32 v[10:11], v[66:67], v[74:75]
	v_pk_mul_f32 v[12:13], v[88:89], v[90:91]
	v_pk_mul_f32 v[18:19], v[66:67], v[84:85]
	v_pk_mul_f32 v[20:21], v[88:89], v[96:97]
	v_pk_mul_f32 v[64:65], v[66:67], v[78:79]
	v_pk_mul_f32 v[66:67], v[88:89], v[86:87]
	v_mov_b32_e32 v120, v6
	v_mov_b32_e32 v121, v14
	v_mov_b32_e32 v122, v7
	v_mov_b32_e32 v123, v15
	v_mov_b32_e32 v124, v10
	v_mov_b32_e32 v125, v18
	v_mov_b32_e32 v126, v11
	v_mov_b32_e32 v127, v19
	v_mov_b32_e32 v128, v8
	v_mov_b32_e32 v129, v16
	v_mov_b32_e32 v130, v9
	v_mov_b32_e32 v131, v17
	v_mov_b32_e32 v132, v12
	v_mov_b32_e32 v133, v20
	v_mov_b32_e32 v134, v13
	v_mov_b32_e32 v135, v21
	ds_write_b128 v76, v[64:67] offset:1024
	s_waitcnt vmcnt(14)
	v_cvt_f32_f16_e32 v14, v68
	v_cvt_f32_f16_sdwa v16, v68 dst_sel:DWORD dst_unused:UNUSED_PAD src0_sel:WORD_1
	v_cvt_f32_f16_e32 v15, v56
	v_cvt_f32_f16_sdwa v17, v56 dst_sel:DWORD dst_unused:UNUSED_PAD src0_sel:WORD_1
	v_cvt_f32_f16_e32 v21, v57
	v_cvt_f32_f16_sdwa v57, v57 dst_sel:DWORD dst_unused:UNUSED_PAD src0_sel:WORD_1
	v_cvt_f32_f16_e32 v20, v69
	v_cvt_f32_f16_sdwa v56, v69 dst_sel:DWORD dst_unused:UNUSED_PAD src0_sel:WORD_1
	v_mov_b32_e32 v8, v14
	v_mov_b32_e32 v9, v16
	v_mov_b32_e32 v6, v15
	v_mov_b32_e32 v7, v17
	v_pk_mul_f32 v[10:11], v[78:79], v[8:9]
	v_mov_b32_e32 v8, v21
	v_mov_b32_e32 v9, v57
	v_pk_mul_f32 v[6:7], v[78:79], v[6:7]
	v_pk_mul_f32 v[8:9], v[86:87], v[8:9]
	v_mov_b32_e32 v12, v20
	v_mov_b32_e32 v13, v56
	v_mov_b32_e32 v18, v83
	v_pk_mul_f32 v[12:13], v[86:87], v[12:13]
	v_mov_b32_e32 v182, v6
	v_mov_b32_e32 v183, v7
	v_mov_b32_e32 v184, v8
	v_mov_b32_e32 v185, v9
	ds_write_b128 v76, v[10:13] offset:1536
	v_pk_fma_f32 v[6:7], v[82:83], v[14:15], 0 op_sel_hi:[0,1,0]
	v_pk_fma_f32 v[6:7], v[18:19], v[16:17], v[6:7] op_sel_hi:[0,1,1]
	v_mov_b32_e32 v10, v75
	v_pk_fma_f32 v[18:19], v[74:75], v[14:15], 0 op_sel_hi:[0,1,0]
	v_pk_fma_f32 v[14:15], v[84:85], v[14:15], 0 op_sel_hi:[0,1,0]
	v_pk_fma_f32 v[10:11], v[10:11], v[16:17], v[18:19] op_sel_hi:[0,1,1]
	v_pk_fma_f32 v[14:15], v[84:85], v[16:17], v[14:15] op_sel:[1,0,0]
	v_mov_b32_e32 v54, v93
	v_pk_fma_f32 v[6:7], v[92:93], v[20:21], v[6:7] op_sel_hi:[0,1,1]
	v_mov_b32_e32 v12, v91
	v_pk_fma_f32 v[10:11], v[90:91], v[20:21], v[10:11] op_sel_hi:[0,1,1]
	v_pk_fma_f32 v[14:15], v[96:97], v[20:21], v[14:15] op_sel_hi:[0,1,1]
	v_pk_fma_f32 v[6:7], v[54:55], v[56:57], v[6:7] op_sel_hi:[0,1,1]
	v_pk_fma_f32 v[10:11], v[12:13], v[56:57], v[10:11] op_sel_hi:[0,1,1]
	v_pk_fma_f32 v[14:15], v[96:97], v[56:57], v[14:15] op_sel:[1,0,0]
	s_waitcnt vmcnt(10)
	v_cvt_f32_f16_e32 v57, v70
	v_cvt_f32_f16_sdwa v65, v70 dst_sel:DWORD dst_unused:UNUSED_PAD src0_sel:WORD_1
	v_cvt_f32_f16_e32 v67, v71
	v_cvt_f32_f16_sdwa v69, v71 dst_sel:DWORD dst_unused:UNUSED_PAD src0_sel:WORD_1
	s_waitcnt vmcnt(9)
	v_cvt_f32_f16_e32 v56, v72
	v_cvt_f32_f16_sdwa v64, v72 dst_sel:DWORD dst_unused:UNUSED_PAD src0_sel:WORD_1
	v_cvt_f32_f16_e32 v66, v73
	v_cvt_f32_f16_sdwa v68, v73 dst_sel:DWORD dst_unused:UNUSED_PAD src0_sel:WORD_1
	v_mov_b32_e32 v18, v57
	v_mov_b32_e32 v19, v65
	v_mov_b32_e32 v20, v67
	v_mov_b32_e32 v21, v69
	ds_write_b128 v76, v[18:21] offset:1792
	v_mov_b32_e32 v18, v56
	v_mov_b32_e32 v19, v64
	v_mov_b32_e32 v20, v66
	v_mov_b32_e32 v21, v68
	v_mov_b32_e32 v54, v81
	ds_write_b128 v76, v[18:21] offset:2048
	v_mov_b32_e32 v186, v18
	v_mov_b32_e32 v187, v19
	v_mov_b32_e32 v188, v20
	v_mov_b32_e32 v189, v21
	v_pk_fma_f32 v[18:19], v[80:81], v[56:57], 0 op_sel_hi:[0,1,0]
	v_pk_fma_f32 v[18:19], v[54:55], v[64:65], v[18:19] op_sel_hi:[0,1,1]
	v_mov_b32_e32 v70, v95
	v_pk_fma_f32 v[18:19], v[94:95], v[66:67], v[18:19] op_sel_hi:[0,1,1]
	v_pk_fma_f32 v[18:19], v[70:71], v[68:69], v[18:19] op_sel_hi:[0,1,1]
	v_mov_b32_dpp v8, v6 row_ror:8 row_mask:0xf bank_mask:0xf bound_ctrl:1
	v_mov_b32_dpp v9, v7 row_ror:8 row_mask:0xf bank_mask:0xf bound_ctrl:1
	v_mov_b32_dpp v12, v10 row_ror:8 row_mask:0xf bank_mask:0xf bound_ctrl:1
	v_mov_b32_dpp v13, v11 row_ror:8 row_mask:0xf bank_mask:0xf bound_ctrl:1
	v_mov_b32_dpp v16, v14 row_ror:8 row_mask:0xf bank_mask:0xf bound_ctrl:1
	v_mov_b32_dpp v17, v15 row_ror:8 row_mask:0xf bank_mask:0xf bound_ctrl:1
	v_mov_b32_dpp v20, v18 row_ror:8 row_mask:0xf bank_mask:0xf bound_ctrl:1
	v_mov_b32_dpp v21, v19 row_ror:8 row_mask:0xf bank_mask:0xf bound_ctrl:1
	v_pk_add_f32 v[6:7], v[6:7], v[8:9]
	v_pk_add_f32 v[10:11], v[10:11], v[12:13]
	v_pk_add_f32 v[14:15], v[14:15], v[16:17]
	v_pk_add_f32 v[18:19], v[18:19], v[20:21]
	v_mov_b32_dpp v8, v6 row_ror:4 row_mask:0xf bank_mask:0xf bound_ctrl:1
	v_mov_b32_dpp v9, v7 row_ror:4 row_mask:0xf bank_mask:0xf bound_ctrl:1
	v_mov_b32_dpp v12, v10 row_ror:4 row_mask:0xf bank_mask:0xf bound_ctrl:1
	v_mov_b32_dpp v13, v11 row_ror:4 row_mask:0xf bank_mask:0xf bound_ctrl:1
	v_mov_b32_dpp v16, v14 row_ror:4 row_mask:0xf bank_mask:0xf bound_ctrl:1
	v_mov_b32_dpp v17, v15 row_ror:4 row_mask:0xf bank_mask:0xf bound_ctrl:1
	v_mov_b32_dpp v20, v18 row_ror:4 row_mask:0xf bank_mask:0xf bound_ctrl:1
	v_mov_b32_dpp v21, v19 row_ror:4 row_mask:0xf bank_mask:0xf bound_ctrl:1
	v_pk_add_f32 v[6:7], v[6:7], v[8:9]
	v_pk_add_f32 v[10:11], v[10:11], v[12:13]
	v_pk_add_f32 v[14:15], v[14:15], v[16:17]
	v_pk_add_f32 v[18:19], v[18:19], v[20:21]
	v_mov_b32_dpp v8, v6 row_ror:2 row_mask:0xf bank_mask:0xf bound_ctrl:1
	v_mov_b32_dpp v9, v7 row_ror:2 row_mask:0xf bank_mask:0xf bound_ctrl:1
	v_mov_b32_dpp v12, v10 row_ror:2 row_mask:0xf bank_mask:0xf bound_ctrl:1
	v_mov_b32_dpp v13, v11 row_ror:2 row_mask:0xf bank_mask:0xf bound_ctrl:1
	v_mov_b32_dpp v16, v14 row_ror:2 row_mask:0xf bank_mask:0xf bound_ctrl:1
	v_mov_b32_dpp v17, v15 row_ror:2 row_mask:0xf bank_mask:0xf bound_ctrl:1
	v_mov_b32_dpp v20, v18 row_ror:2 row_mask:0xf bank_mask:0xf bound_ctrl:1
	v_mov_b32_dpp v21, v19 row_ror:2 row_mask:0xf bank_mask:0xf bound_ctrl:1
	v_pk_add_f32 v[6:7], v[6:7], v[8:9]
	v_pk_add_f32 v[10:11], v[10:11], v[12:13]
	v_pk_add_f32 v[14:15], v[14:15], v[16:17]
	v_pk_add_f32 v[18:19], v[18:19], v[20:21]
	v_mov_b32_dpp v8, v6 row_ror:1 row_mask:0xf bank_mask:0xf bound_ctrl:1
	v_mov_b32_dpp v9, v7 row_ror:1 row_mask:0xf bank_mask:0xf bound_ctrl:1
	v_mov_b32_dpp v12, v10 row_ror:1 row_mask:0xf bank_mask:0xf bound_ctrl:1
	v_mov_b32_dpp v13, v11 row_ror:1 row_mask:0xf bank_mask:0xf bound_ctrl:1
	v_mov_b32_dpp v16, v14 row_ror:1 row_mask:0xf bank_mask:0xf bound_ctrl:1
	v_mov_b32_dpp v17, v15 row_ror:1 row_mask:0xf bank_mask:0xf bound_ctrl:1
	v_mov_b32_dpp v20, v18 row_ror:1 row_mask:0xf bank_mask:0xf bound_ctrl:1
	v_mov_b32_dpp v21, v19 row_ror:1 row_mask:0xf bank_mask:0xf bound_ctrl:1
	s_and_saveexec_b64 s[22:23], s[0:1]
	s_cbranch_execz .LBB0_661
	v_pk_add_f32 v[6:7], v[6:7], v[8:9]
	v_pk_add_f32 v[8:9], v[10:11], v[12:13]
	s_mov_b32 s10, 0x3d800000
	v_pk_mul_f32 v[8:9], v[8:9], s[10:11] op_sel_hi:[1,0]
	v_add_u32_e32 v10, 0x1ab00, v77
	ds_write_b128 v10, v[6:9]
	v_pk_add_f32 v[6:7], v[14:15], v[16:17]
	v_pk_add_f32 v[8:9], v[18:19], v[20:21]
	v_pk_mul_f32 v[6:7], v[6:7], s[10:11] op_sel_hi:[1,0]
	v_pk_mul_f32 v[8:9], v[8:9], s[10:11] op_sel_hi:[1,0]
	ds_write_b128 v10, v[6:9] offset:16
.LBB0_661:
	s_or_b64 exec, exec, s[22:23]
	v_lshlrev_b32_e32 v6, 2, v60
	s_add_i32 s7, 0, 0x1ae00
	v_add3_u32 v78, s7, v6, v24
	s_add_u32 s7, s20, s6
	s_addc_u32 s9, s21, 0
	s_add_u32 s20, s7, s8
	s_waitcnt vmcnt(3)
	v_cvt_f32_f16_sdwa v7, v22 dst_sel:DWORD dst_unused:UNUSED_PAD src0_sel:WORD_1
	v_cvt_f32_f16_e32 v6, v22
	s_addc_u32 s21, s9, 0
	v_lshl_add_u64 v[56:57], s[20:21], 0, v[2:3]
	s_mov_b64 s[20:21], 0x18000
	v_or_b32_e32 v54, 0x400, v55
	v_lshl_add_u64 v[16:17], v[28:29], 0, s[20:21]
	ds_write_b64 v78, v[6:7]
	ds_read_b128 v[198:201], v217 offset:36864
	ds_read_b128 v[202:205], v217 offset:36880
	ds_read2_b32 v[206:207], v221 offset1:16
	s_waitcnt lgkmcnt(0)
	v_mul_f32_e32 v210, 0x41800000, v200
	v_mul_f32_e32 v211, 0x41800000, v202
	v_mul_f32_e32 v212, 0x41800000, v204
	v_fma_f32 v213, -v204, v199, v203
	v_fma_f32 v121, -v198, v120, v121
	v_fma_f32 v124, -v210, v120, v124
	v_fma_f32 v125, -v211, v120, v125
	v_fma_f32 v123, -v198, v122, v123
	v_fma_f32 v126, -v210, v122, v126
	v_fma_f32 v127, -v211, v122, v127
	v_fma_f32 v129, -v198, v128, v129
	v_fma_f32 v132, -v210, v128, v132
	v_fma_f32 v133, -v211, v128, v133
	v_fma_f32 v131, -v198, v130, v131
	v_fma_f32 v134, -v210, v130, v134
	v_fma_f32 v135, -v211, v130, v135
	v_fma_f32 v182, -v199, v186, v182
	v_fma_f32 v183, -v199, v187, v183
	v_fma_f32 v184, -v199, v188, v184
	v_fma_f32 v185, -v199, v189, v185
	v_fma_f32 v125, -v212, v121, v125
	v_fma_f32 v127, -v212, v123, v127
	v_fma_f32 v133, -v212, v129, v133
	v_fma_f32 v135, -v212, v131, v135
	v_mul_f32_e32 v208, v206, v201
	v_mul_f32_e32 v209, v206, v213
	ds_write_b128 v219, v[120:123]
	v_fmac_f32_e32 v209, v207, v205
	ds_write_b128 v219, v[124:127] offset:256
	ds_write_b128 v219, v[128:131] offset:512
	ds_write_b128 v219, v[132:135] offset:768
	ds_write_b128 v219, v[182:185] offset:1280
	ds_write_b128 v223, v[206:209]
	v_or_b32_e32 v6, v16, v55
	v_mov_b32_e32 v7, v17
	v_or_b32_e32 v16, v16, v54
	v_lshlrev_b64 v[12:13], 1, v[6:7]
	v_lshlrev_b64 v[22:23], 1, v[16:17]
	v_lshl_add_u64 v[56:57], v[56:57], 0, v[32:33]
	s_mov_b32 s7, 0x30000
	v_lshl_add_u64 v[6:7], s[70:71], 0, v[12:13]
	v_lshl_add_u64 v[8:9], s[12:13], 0, v[12:13]
	v_lshl_add_u64 v[10:11], s[14:15], 0, v[12:13]
	v_lshl_add_u64 v[14:15], s[16:17], 0, v[12:13]
	v_lshl_add_u64 v[18:19], s[18:19], 0, v[12:13]
	v_lshl_add_u64 v[16:17], s[70:71], 0, v[22:23]
	v_lshl_add_u64 v[20:21], s[12:13], 0, v[22:23]
	v_lshl_add_u64 v[24:25], s[14:15], 0, v[22:23]
	v_add_co_u32_e32 v32, vcc, s7, v56
	global_load_dwordx2 v[6:7], v[6:7], off
	s_nop 0
	global_load_dwordx2 v[8:9], v[8:9], off
	s_nop 0
	global_load_dwordx2 v[10:11], v[10:11], off
	s_nop 0
	global_load_dwordx2 v[12:13], v[14:15], off
	s_nop 0
	global_load_dwordx2 v[14:15], v[18:19], off
	s_nop 0
	global_load_dwordx2 v[18:19], v[16:17], off
	s_nop 0
	global_load_dwordx2 v[16:17], v[20:21], off
	s_nop 0
	global_load_dwordx2 v[20:21], v[24:25], off
	v_lshl_add_u64 v[24:25], s[16:17], 0, v[22:23]
	v_lshl_add_u64 v[22:23], s[18:19], 0, v[22:23]
	v_addc_co_u32_e32 v33, vcc, 0, v57, vcc
	global_load_dwordx2 v[24:25], v[24:25], off
	s_nop 0
	global_load_dwordx2 v[22:23], v[22:23], off
	v_cvt_f32_f16_sdwa v67, v50 dst_sel:DWORD dst_unused:UNUSED_PAD src0_sel:WORD_1
	global_load_dword v79, v[32:33], off
	v_cvt_f32_f16_e32 v66, v50
	v_cvt_f32_f16_sdwa v33, v52 dst_sel:DWORD dst_unused:UNUSED_PAD src0_sel:WORD_1
	v_cvt_f32_f16_e32 v32, v52
	v_cvt_f32_f16_sdwa v71, v53 dst_sel:DWORD dst_unused:UNUSED_PAD src0_sel:WORD_1
	v_cvt_f32_f16_e32 v70, v53
	s_waitcnt vmcnt(12)
	v_cvt_f32_f16_sdwa v75, v44 dst_sel:DWORD dst_unused:UNUSED_PAD src0_sel:WORD_1
	v_cvt_f32_f16_e32 v74, v44
	v_cvt_f32_f16_sdwa v53, v51 dst_sel:DWORD dst_unused:UNUSED_PAD src0_sel:WORD_1
	v_cvt_f32_f16_e32 v52, v51
	v_cvt_f32_f16_sdwa v93, v45 dst_sel:DWORD dst_unused:UNUSED_PAD src0_sel:WORD_1
	v_cvt_f32_f16_e32 v92, v45
	v_cvt_f32_f16_sdwa v65, v42 dst_sel:DWORD dst_unused:UNUSED_PAD src0_sel:WORD_1
	v_cvt_f32_f16_e32 v64, v42
	v_pk_add_f32 v[68:69], v[66:67], 1.0 op_sel_hi:[1,0] neg_lo:[1,0] neg_hi:[1,0]
	v_cvt_f32_f16_sdwa v73, v48 dst_sel:DWORD dst_unused:UNUSED_PAD src0_sel:WORD_1
	v_cvt_f32_f16_e32 v72, v48
	v_cvt_f32_f16_sdwa v83, v46 dst_sel:DWORD dst_unused:UNUSED_PAD src0_sel:WORD_1
	v_cvt_f32_f16_e32 v82, v46
	v_cvt_f32_f16_sdwa v67, v43 dst_sel:DWORD dst_unused:UNUSED_PAD src0_sel:WORD_1
	v_cvt_f32_f16_e32 v66, v43
	v_cvt_f32_f16_sdwa v89, v49 dst_sel:DWORD dst_unused:UNUSED_PAD src0_sel:WORD_1
	v_cvt_f32_f16_e32 v88, v49
	v_cvt_f32_f16_sdwa v91, v47 dst_sel:DWORD dst_unused:UNUSED_PAD src0_sel:WORD_1
	v_cvt_f32_f16_e32 v90, v47
	v_pk_add_f32 v[32:33], v[32:33], 1.0 op_sel_hi:[1,0] neg_lo:[1,0] neg_hi:[1,0]
	v_pk_add_f32 v[86:87], v[70:71], 1.0 op_sel_hi:[1,0] neg_lo:[1,0] neg_hi:[1,0]
	v_pk_mul_f32 v[84:85], v[32:33], v[74:75]
	v_pk_add_f32 v[70:71], v[52:53], 1.0 op_sel_hi:[1,0] neg_lo:[1,0] neg_hi:[1,0]
	v_pk_mul_f32 v[94:95], v[86:87], v[92:93]
	v_pk_mul_f32 v[50:51], v[68:69], v[84:85]
	v_pk_mul_f32 v[52:53], v[70:71], v[94:95]
	v_add_u32_e32 v80, v59, v62
	s_waitcnt lgkmcnt(0)
	s_cselect_b32 s62, 1, 0
	s_add_i32 s61, s61, 1
	s_waitcnt lgkmcnt(0)
	v_mov_b32_e32 v226, s61
	s_mov_b64 s[58:59], exec
	s_mov_b64 exec, 1
	ds_write_b32 v224, v226
	s_mov_b64 exec, s[58:59]
	s_sub_i32 s63, s61, 1
.Lst_wait_1:
	ds_read_b128 v[228:231], v225
	s_waitcnt lgkmcnt(0)
	v_min_u32_e32 v228, v228, v229
	v_min_u32_e32 v230, v230, v231
	v_min_u32_e32 v228, v228, v230
	s_nop 0
	v_readfirstlane_b32 s60, v228
	s_nop 3
	s_cmp_ge_u32 s60, s63
	s_cbranch_scc1 .Lst_go_1
	s_sleep 1
	s_branch .Lst_wait_1
.Lst_go_1:
	s_cmp_lg_u32 s62, 0
	v_pk_mul_f32 v[42:43], v[68:69], v[72:73]
	v_pk_mul_f32 v[44:45], v[70:71], v[88:89]
	v_pk_mul_f32 v[46:47], v[68:69], v[82:83]
	v_pk_mul_f32 v[48:49], v[70:71], v[90:91]
	v_pk_mul_f32 v[68:69], v[68:69], v[32:33]
	v_pk_mul_f32 v[70:71], v[70:71], v[86:87]
	v_mov_b32_e32 v120, v64
	v_mov_b32_e32 v121, v46
	v_mov_b32_e32 v122, v65
	v_mov_b32_e32 v123, v47
	v_mov_b32_e32 v124, v42
	v_mov_b32_e32 v125, v50
	v_mov_b32_e32 v126, v43
	v_mov_b32_e32 v127, v51
	v_mov_b32_e32 v128, v66
	v_mov_b32_e32 v129, v48
	v_mov_b32_e32 v130, v67
	v_mov_b32_e32 v131, v49
	v_mov_b32_e32 v132, v44
	v_mov_b32_e32 v133, v52
	v_mov_b32_e32 v134, v45
	v_mov_b32_e32 v135, v53
	ds_write_b128 v80, v[68:71] offset:1024
	v_cvt_f32_f16_e32 v51, v38
	v_cvt_f32_f16_sdwa v53, v38 dst_sel:DWORD dst_unused:UNUSED_PAD src0_sel:WORD_1
	v_cvt_f32_f16_e32 v50, v40
	v_cvt_f32_f16_sdwa v52, v40 dst_sel:DWORD dst_unused:UNUSED_PAD src0_sel:WORD_1
	v_cvt_f32_f16_e32 v63, v39
	v_cvt_f32_f16_sdwa v65, v39 dst_sel:DWORD dst_unused:UNUSED_PAD src0_sel:WORD_1
	v_cvt_f32_f16_e32 v62, v41
	v_cvt_f32_f16_sdwa v64, v41 dst_sel:DWORD dst_unused:UNUSED_PAD src0_sel:WORD_1
	v_mov_b32_e32 v42, v51
	v_mov_b32_e32 v43, v53
	v_mov_b32_e32 v44, v50
	v_mov_b32_e32 v45, v52
	v_mov_b32_e32 v38, v63
	v_mov_b32_e32 v39, v65
	v_pk_mul_f32 v[42:43], v[32:33], v[42:43]
	v_pk_mul_f32 v[46:47], v[32:33], v[44:45]
	v_mov_b32_e32 v32, v83
	v_pk_mul_f32 v[44:45], v[86:87], v[38:39]
	v_mov_b32_e32 v38, v62
	v_mov_b32_e32 v39, v64
	v_pk_fma_f32 v[40:41], v[82:83], v[50:51], 0 op_sel_hi:[0,1,0]
	v_pk_mul_f32 v[48:49], v[86:87], v[38:39]
	v_mov_b32_e32 v182, v42
	v_mov_b32_e32 v183, v43
	v_mov_b32_e32 v184, v44
	v_mov_b32_e32 v185, v45
	ds_write_b128 v80, v[46:49] offset:1536
	v_pk_fma_f32 v[32:33], v[32:33], v[52:53], v[40:41] op_sel_hi:[0,1,1]
	v_mov_b32_e32 v40, v73
	v_pk_fma_f32 v[44:45], v[72:73], v[50:51], 0 op_sel_hi:[0,1,0]
	v_pk_fma_f32 v[40:41], v[40:41], v[52:53], v[44:45] op_sel_hi:[0,1,1]
	v_pk_fma_f32 v[44:45], v[84:85], v[50:51], 0 op_sel_hi:[0,1,0]
	v_pk_fma_f32 v[44:45], v[84:85], v[52:53], v[44:45] op_sel:[1,0,0]
	v_mov_b32_e32 v38, v91
	v_pk_fma_f32 v[32:33], v[90:91], v[62:63], v[32:33] op_sel_hi:[0,1,1]
	v_mov_b32_e32 v42, v89
	v_pk_fma_f32 v[40:41], v[88:89], v[62:63], v[40:41] op_sel_hi:[0,1,1]
	v_pk_fma_f32 v[44:45], v[94:95], v[62:63], v[44:45] op_sel_hi:[0,1,1]
	v_pk_fma_f32 v[32:33], v[38:39], v[64:65], v[32:33] op_sel_hi:[0,1,1]
	v_pk_fma_f32 v[40:41], v[42:43], v[64:65], v[40:41] op_sel_hi:[0,1,1]
	v_pk_fma_f32 v[44:45], v[94:95], v[64:65], v[44:45] op_sel:[1,0,0]
	v_cvt_f32_f16_e32 v49, v34
	v_cvt_f32_f16_sdwa v51, v34 dst_sel:DWORD dst_unused:UNUSED_PAD src0_sel:WORD_1
	v_cvt_f32_f16_e32 v63, v35
	v_cvt_f32_f16_sdwa v65, v35 dst_sel:DWORD dst_unused:UNUSED_PAD src0_sel:WORD_1
	v_cvt_f32_f16_e32 v48, v36
	v_cvt_f32_f16_sdwa v50, v36 dst_sel:DWORD dst_unused:UNUSED_PAD src0_sel:WORD_1
	v_cvt_f32_f16_e32 v62, v37
	v_cvt_f32_f16_sdwa v64, v37 dst_sel:DWORD dst_unused:UNUSED_PAD src0_sel:WORD_1
	v_mov_b32_e32 v34, v49
	v_mov_b32_e32 v35, v51
	v_mov_b32_e32 v36, v63
	v_mov_b32_e32 v37, v65
	ds_write_b128 v80, v[34:37] offset:1792
	v_mov_b32_e32 v34, v48
	v_mov_b32_e32 v35, v50
	v_mov_b32_e32 v36, v62
	v_mov_b32_e32 v37, v64
	v_mov_b32_e32 v52, v75
	ds_write_b128 v80, v[34:37] offset:2048
	v_mov_b32_e32 v186, v34
	v_mov_b32_e32 v187, v35
	v_mov_b32_e32 v188, v36
	v_mov_b32_e32 v189, v37
	v_pk_fma_f32 v[34:35], v[74:75], v[48:49], 0 op_sel_hi:[0,1,0]
	v_pk_fma_f32 v[34:35], v[52:53], v[50:51], v[34:35] op_sel_hi:[0,1,1]
	v_mov_b32_e32 v66, v93
	v_pk_fma_f32 v[34:35], v[92:93], v[62:63], v[34:35] op_sel_hi:[0,1,1]
	v_pk_fma_f32 v[34:35], v[66:67], v[64:65], v[34:35] op_sel_hi:[0,1,1]
	v_mov_b32_dpp v38, v32 row_ror:8 row_mask:0xf bank_mask:0xf bound_ctrl:1
	v_mov_b32_dpp v39, v33 row_ror:8 row_mask:0xf bank_mask:0xf bound_ctrl:1
	v_mov_b32_dpp v42, v40 row_ror:8 row_mask:0xf bank_mask:0xf bound_ctrl:1
	v_mov_b32_dpp v43, v41 row_ror:8 row_mask:0xf bank_mask:0xf bound_ctrl:1
	v_mov_b32_dpp v46, v44 row_ror:8 row_mask:0xf bank_mask:0xf bound_ctrl:1
	v_mov_b32_dpp v47, v45 row_ror:8 row_mask:0xf bank_mask:0xf bound_ctrl:1
	v_mov_b32_dpp v36, v34 row_ror:8 row_mask:0xf bank_mask:0xf bound_ctrl:1
	v_mov_b32_dpp v37, v35 row_ror:8 row_mask:0xf bank_mask:0xf bound_ctrl:1
	v_pk_add_f32 v[32:33], v[32:33], v[38:39]
	v_pk_add_f32 v[40:41], v[40:41], v[42:43]
	v_pk_add_f32 v[44:45], v[44:45], v[46:47]
	v_pk_add_f32 v[34:35], v[34:35], v[36:37]
	v_mov_b32_dpp v38, v32 row_ror:4 row_mask:0xf bank_mask:0xf bound_ctrl:1
	v_mov_b32_dpp v39, v33 row_ror:4 row_mask:0xf bank_mask:0xf bound_ctrl:1
	v_mov_b32_dpp v42, v40 row_ror:4 row_mask:0xf bank_mask:0xf bound_ctrl:1
	v_mov_b32_dpp v43, v41 row_ror:4 row_mask:0xf bank_mask:0xf bound_ctrl:1
	v_mov_b32_dpp v46, v44 row_ror:4 row_mask:0xf bank_mask:0xf bound_ctrl:1
	v_mov_b32_dpp v47, v45 row_ror:4 row_mask:0xf bank_mask:0xf bound_ctrl:1
	v_mov_b32_dpp v36, v34 row_ror:4 row_mask:0xf bank_mask:0xf bound_ctrl:1
	v_mov_b32_dpp v37, v35 row_ror:4 row_mask:0xf bank_mask:0xf bound_ctrl:1
	v_pk_add_f32 v[32:33], v[32:33], v[38:39]
	v_pk_add_f32 v[40:41], v[40:41], v[42:43]
	v_pk_add_f32 v[44:45], v[44:45], v[46:47]
	v_pk_add_f32 v[34:35], v[34:35], v[36:37]
	v_mov_b32_dpp v38, v32 row_ror:2 row_mask:0xf bank_mask:0xf bound_ctrl:1
	v_mov_b32_dpp v39, v33 row_ror:2 row_mask:0xf bank_mask:0xf bound_ctrl:1
	v_mov_b32_dpp v42, v40 row_ror:2 row_mask:0xf bank_mask:0xf bound_ctrl:1
	v_mov_b32_dpp v43, v41 row_ror:2 row_mask:0xf bank_mask:0xf bound_ctrl:1
	v_mov_b32_dpp v46, v44 row_ror:2 row_mask:0xf bank_mask:0xf bound_ctrl:1
	v_mov_b32_dpp v47, v45 row_ror:2 row_mask:0xf bank_mask:0xf bound_ctrl:1
	v_mov_b32_dpp v36, v34 row_ror:2 row_mask:0xf bank_mask:0xf bound_ctrl:1
	v_mov_b32_dpp v37, v35 row_ror:2 row_mask:0xf bank_mask:0xf bound_ctrl:1
	v_pk_add_f32 v[32:33], v[32:33], v[38:39]
	v_pk_add_f32 v[40:41], v[40:41], v[42:43]
	v_pk_add_f32 v[44:45], v[44:45], v[46:47]
	v_pk_add_f32 v[34:35], v[34:35], v[36:37]
	v_mov_b32_dpp v38, v32 row_ror:1 row_mask:0xf bank_mask:0xf bound_ctrl:1
	v_mov_b32_dpp v39, v33 row_ror:1 row_mask:0xf bank_mask:0xf bound_ctrl:1
	v_mov_b32_dpp v42, v40 row_ror:1 row_mask:0xf bank_mask:0xf bound_ctrl:1
	v_mov_b32_dpp v43, v41 row_ror:1 row_mask:0xf bank_mask:0xf bound_ctrl:1
	v_mov_b32_dpp v46, v44 row_ror:1 row_mask:0xf bank_mask:0xf bound_ctrl:1
	v_mov_b32_dpp v47, v45 row_ror:1 row_mask:0xf bank_mask:0xf bound_ctrl:1
	v_mov_b32_dpp v36, v34 row_ror:1 row_mask:0xf bank_mask:0xf bound_ctrl:1
	v_mov_b32_dpp v37, v35 row_ror:1 row_mask:0xf bank_mask:0xf bound_ctrl:1
	s_and_saveexec_b64 s[20:21], s[0:1]
	s_cbranch_execz .LBB0_663
	v_pk_add_f32 v[38:39], v[32:33], v[38:39]
	v_pk_add_f32 v[32:33], v[40:41], v[42:43]
	s_mov_b32 s10, 0x3d800000
	v_pk_mul_f32 v[40:41], v[32:33], s[10:11] op_sel_hi:[1,0]
	v_pk_add_f32 v[32:33], v[44:45], v[46:47]
	v_pk_add_f32 v[34:35], v[34:35], v[36:37]
	v_pk_mul_f32 v[32:33], v[32:33], s[10:11] op_sel_hi:[1,0]
	v_pk_mul_f32 v[34:35], v[34:35], s[10:11] op_sel_hi:[1,0]
	ds_write_b128 v77, v[38:41] offset:36864
	ds_write_b128 v77, v[32:35] offset:36880
.LBB0_663:
	s_or_b64 exec, exec, s[20:21]
	s_add_u32 s20, s78, 0xf000000
	s_addc_u32 s21, s79, 0
	s_add_u32 s7, s20, s6
	s_addc_u32 s9, s21, 0
	s_add_u32 s22, s7, s8
	s_addc_u32 s23, s9, 0
	v_mov_b32_e32 v3, 0
	s_waitcnt vmcnt(11)
	v_cvt_f32_f16_sdwa v35, v61 dst_sel:DWORD dst_unused:UNUSED_PAD src0_sel:WORD_1
	v_cvt_f32_f16_e32 v34, v61
	v_lshl_add_u64 v[32:33], s[22:23], 0, v[2:3]
	s_mov_b64 s[22:23], 0x20000
	v_lshl_add_u64 v[38:39], v[28:29], 0, s[22:23]
	v_or_b32_e32 v28, v38, v55
	v_mov_b32_e32 v29, v39
	v_or_b32_e32 v38, v38, v54
	v_lshlrev_b64 v[30:31], 12, v[30:31]
	ds_write_b64 v1, v[34:35] offset:37632
	ds_read_b128 v[198:201], v216 offset:36864
	ds_read_b128 v[202:205], v216 offset:36880
	ds_read2_b32 v[206:207], v220 offset1:16
	s_waitcnt lgkmcnt(0)
	v_mul_f32_e32 v210, 0x41800000, v200
	v_mul_f32_e32 v211, 0x41800000, v202
	v_mul_f32_e32 v212, 0x41800000, v204
	v_fma_f32 v213, -v204, v199, v203
	v_fma_f32 v121, -v198, v120, v121
	v_fma_f32 v124, -v210, v120, v124
	v_fma_f32 v125, -v211, v120, v125
	v_fma_f32 v123, -v198, v122, v123
	v_fma_f32 v126, -v210, v122, v126
	v_fma_f32 v127, -v211, v122, v127
	v_fma_f32 v129, -v198, v128, v129
	v_fma_f32 v132, -v210, v128, v132
	v_fma_f32 v133, -v211, v128, v133
	v_fma_f32 v131, -v198, v130, v131
	v_fma_f32 v134, -v210, v130, v134
	v_fma_f32 v135, -v211, v130, v135
	v_fma_f32 v182, -v199, v186, v182
	v_fma_f32 v183, -v199, v187, v183
	v_fma_f32 v184, -v199, v188, v184
	v_fma_f32 v185, -v199, v189, v185
	v_fma_f32 v125, -v212, v121, v125
	v_fma_f32 v127, -v212, v123, v127
	v_fma_f32 v133, -v212, v129, v133
	v_fma_f32 v135, -v212, v131, v135
	v_mul_f32_e32 v208, v206, v201
	v_mul_f32_e32 v209, v206, v213
	ds_write_b128 v218, v[120:123]
	v_fmac_f32_e32 v209, v207, v205
	ds_write_b128 v218, v[124:127] offset:256
	ds_write_b128 v218, v[128:131] offset:512
	ds_write_b128 v218, v[132:135] offset:768
	ds_write_b128 v218, v[182:185] offset:1280
	ds_write_b128 v222, v[206:209]
	v_lshlrev_b64 v[34:35], 1, v[28:29]
	v_lshlrev_b64 v[44:45], 1, v[38:39]
	s_mov_b32 s7, 0x40000
	v_lshl_add_u64 v[52:53], v[32:33], 0, v[30:31]
	v_lshl_add_u64 v[28:29], s[70:71], 0, v[34:35]
	v_lshl_add_u64 v[30:31], s[12:13], 0, v[34:35]
	v_lshl_add_u64 v[32:33], s[14:15], 0, v[34:35]
	v_lshl_add_u64 v[36:37], s[16:17], 0, v[34:35]
	v_lshl_add_u64 v[40:41], s[18:19], 0, v[34:35]
	v_lshl_add_u64 v[38:39], s[70:71], 0, v[44:45]
	v_lshl_add_u64 v[42:43], s[12:13], 0, v[44:45]
	v_lshl_add_u64 v[46:47], s[14:15], 0, v[44:45]
	v_add_co_u32_e32 v48, vcc, s7, v56
	global_load_dwordx2 v[28:29], v[28:29], off
	s_nop 0
	global_load_dwordx2 v[30:31], v[30:31], off
	s_nop 0
	global_load_dwordx2 v[32:33], v[32:33], off
	s_nop 0
	global_load_dwordx2 v[34:35], v[36:37], off
	s_nop 0
	global_load_dwordx2 v[36:37], v[40:41], off
	s_nop 0
	global_load_dwordx2 v[40:41], v[38:39], off
	s_nop 0
	global_load_dwordx2 v[38:39], v[42:43], off
	s_nop 0
	global_load_dwordx2 v[42:43], v[46:47], off
	v_lshl_add_u64 v[46:47], s[16:17], 0, v[44:45]
	v_lshl_add_u64 v[44:45], s[18:19], 0, v[44:45]
	v_addc_co_u32_e32 v49, vcc, 0, v57, vcc
	global_load_dwordx2 v[46:47], v[46:47], off
	s_nop 0
	global_load_dwordx2 v[44:45], v[44:45], off
	v_or_b32_e32 v3, v60, v58
	global_load_dword v81, v[48:49], off
	v_lshlrev_b32_e32 v3, 6, v3
	v_add_u32_e32 v3, 0, v3
	v_bfe_u32 v177, v152, 4, 1
	v_sub_u32_e32 v176, 0, v177
	v_lshlrev_b32_e32 v178, 6, v177
	v_sub_u32_e32 v179, 64, v178
	v_bfe_u32 v177, v152, 1, 2
	v_add_u32_e32 v180, 0, v177
	v_and_b32_e32 v180, 3, v180
	v_lshlrev_b32_e32 v180, 4, v180
	v_add3_u32 v160, v3, v178, v180
	v_add3_u32 v164, v3, v179, v180
	v_add_u32_e32 v180, 1, v177
	v_and_b32_e32 v180, 3, v180
	v_lshlrev_b32_e32 v180, 4, v180
	v_add3_u32 v161, v3, v178, v180
	v_add3_u32 v165, v3, v179, v180
	v_add_u32_e32 v180, 2, v177
	v_and_b32_e32 v180, 3, v180
	v_lshlrev_b32_e32 v180, 4, v180
	v_add3_u32 v162, v3, v178, v180
	v_add3_u32 v166, v3, v179, v180
	v_add_u32_e32 v180, 3, v177
	v_and_b32_e32 v180, 3, v180
	v_lshlrev_b32_e32 v180, 4, v180
	v_add3_u32 v163, v3, v178, v180
	v_add3_u32 v167, v3, v179, v180
	v_add_u32_e32 v168, 0x11b00, v160
	v_add_u32_e32 v169, 0x11b00, v161
	v_add_u32_e32 v170, 0x11b00, v162
	v_add_u32_e32 v171, 0x11b00, v163
	v_add_u32_e32 v172, 0x11b00, v164
	v_add_u32_e32 v173, 0x11b00, v165
	v_add_u32_e32 v174, 0x11b00, v166
	v_add_u32_e32 v175, 0x11b00, v167
	ds_read_b128 v[120:123], v160 offset:39680
	ds_read_b128 v[124:127], v161 offset:39680
	ds_read_b128 v[128:131], v162 offset:39680
	ds_read_b128 v[132:135], v163 offset:39680
	ds_read_b128 v[136:139], v164 offset:39680
	ds_read_b128 v[140:143], v165 offset:39680
	ds_read_b128 v[144:147], v166 offset:39680
	ds_read_b128 v[148:151], v167 offset:39680
	s_movk_i32 s7, 0x7fff
	v_mov_b32_e32 v82, 1
	s_mov_b32 s9, 0xffff0000
	s_lshl_b32 s10, s2, 20
	s_and_b32 s10, s10, 0x4000000
	s_waitcnt lgkmcnt(0)
	v_pk_add_f32 v[120:121], v[120:121], v[124:125]
	v_pk_add_f32 v[122:123], v[122:123], v[126:127]
	v_pk_add_f32 v[128:129], v[128:129], v[132:133]
	v_pk_add_f32 v[130:131], v[130:131], v[134:135]
	v_pk_add_f32 v[120:121], v[120:121], v[128:129]
	v_pk_add_f32 v[122:123], v[122:123], v[130:131]
	v_pk_add_f32 v[120:121], v[120:121], v[122:123]
	v_add_f32_e32 v120, v120, v121
	v_pk_add_f32 v[136:137], v[136:137], v[140:141]
	v_pk_add_f32 v[138:139], v[138:139], v[142:143]
	v_pk_add_f32 v[144:145], v[144:145], v[148:149]
	v_pk_add_f32 v[146:147], v[146:147], v[150:151]
	v_pk_add_f32 v[136:137], v[136:137], v[144:145]
	v_pk_add_f32 v[138:139], v[138:139], v[146:147]
	v_pk_add_f32 v[136:137], v[136:137], v[138:139]
	v_add_f32_e32 v136, v136, v137
	v_bfi_b32 v49, v176, v136, v120
	v_bfi_b32 v48, v176, v120, v136
	v_and_b32_sdwa v50, v49, v82 dst_sel:DWORD dst_unused:UNUSED_PAD src0_sel:WORD_1 src1_sel:DWORD
	v_and_b32_sdwa v51, v48, v82 dst_sel:DWORD dst_unused:UNUSED_PAD src0_sel:WORD_1 src1_sel:DWORD
	v_add3_u32 v49, v49, v50, s7
	v_add3_u32 v48, v48, v51, s7
	v_lshrrev_b32_e32 v49, 16, v49
	v_and_or_b32 v48, v48, s9, v49
	global_store_dword v[52:53], v48, off
	v_lshlrev_b64 v[48:49], 12, v[4:5]
	v_lshl_add_u64 v[48:49], s[10:11], 0, v[48:49]
	s_lshl_b32 s10, s25, 5
	v_and_b32_e32 v50, 7, v153
	s_and_b32 s14, s10, 0x780
	v_lshlrev_b32_e32 v52, 2, v50
	v_lshlrev_b64 v[50:51], 11, v[4:5]
	v_or_b32_e32 v48, s14, v48
	s_and_b32 s15, s24, 0x60
	v_or_b32_e32 v50, s14, v50
	v_or3_b32 v48, v48, s15, v52
	v_or3_b32 v50, v50, s15, v52
	v_lshlrev_b64 v[52:53], 11, v[26:27]
	v_lshl_add_u64 v[48:49], s[78:79], 0, v[48:49]
	s_mov_b64 s[12:13], 0xf040000
	s_lshl_b32 s10, s2, 19
	v_lshl_or_b32 v52, v55, 1, v52
	v_lshl_add_u64 v[48:49], v[48:49], 0, s[12:13]
	s_and_b32 s10, s10, 0x2000000
	v_lshl_add_u64 v[50:51], s[70:71], 0, v[50:51]
	v_lshl_add_u64 v[26:27], s[70:71], 0, v[52:53]
	v_lshl_add_u64 v[52:53], s[78:79], 0, v[52:53]
	s_mov_b32 s12, 0x3d800000
	s_mov_b64 s[14:15], 0x40000
	s_mov_b32 s13, s11
	s_cselect_b32 s62, 1, 0
	s_add_i32 s61, s61, 1
	s_waitcnt lgkmcnt(0)
	v_mov_b32_e32 v226, s61
	s_mov_b64 s[58:59], exec
	s_mov_b64 exec, 1
	ds_write_b32 v224, v226
	s_mov_b64 exec, s[58:59]
	s_sub_i32 s63, s61, 1

.Lst_go_2:
	s_cmp_lg_u32 s62, 0
	s_branch .LBB0_665
.LBB0_664:
	ds_read_b128 v[120:123], v160 offset:39680
	ds_read_b128 v[124:127], v161 offset:39680
	ds_read_b128 v[128:131], v162 offset:39680
	ds_read_b128 v[132:135], v163 offset:39680
	ds_read_b128 v[136:139], v164 offset:39680
	ds_read_b128 v[140:143], v165 offset:39680
	ds_read_b128 v[144:147], v166 offset:39680
	ds_read_b128 v[148:151], v167 offset:39680
	v_lshl_add_u64 v[50:51], v[50:51], 0, s[22:23]
	v_lshl_add_u64 v[26:27], v[26:27], 0, s[22:23]
	v_lshl_add_u64 v[52:53], v[52:53], 0, s[22:23]
	s_and_b64 vcc, exec, s[16:17]
	s_nop 0
	s_waitcnt lgkmcnt(0)
	v_pk_add_f32 v[120:121], v[120:121], v[124:125]
	v_pk_add_f32 v[122:123], v[122:123], v[126:127]
	v_pk_add_f32 v[128:129], v[128:129], v[132:133]
	v_pk_add_f32 v[130:131], v[130:131], v[134:135]
	v_pk_add_f32 v[120:121], v[120:121], v[128:129]
	v_pk_add_f32 v[122:123], v[122:123], v[130:131]
	v_pk_add_f32 v[120:121], v[120:121], v[122:123]
	v_add_f32_e32 v120, v120, v121
	v_pk_add_f32 v[136:137], v[136:137], v[140:141]
	v_pk_add_f32 v[138:139], v[138:139], v[142:143]
	v_pk_add_f32 v[144:145], v[144:145], v[148:149]
	v_pk_add_f32 v[146:147], v[146:147], v[150:151]
	v_pk_add_f32 v[136:137], v[136:137], v[144:145]
	v_pk_add_f32 v[138:139], v[138:139], v[146:147]
	v_pk_add_f32 v[136:137], v[136:137], v[138:139]
	v_add_f32_e32 v136, v136, v137
	v_bfi_b32 v55, v176, v136, v120
	v_bfi_b32 v54, v176, v120, v136
	v_and_b32_sdwa v56, v55, v82 dst_sel:DWORD dst_unused:UNUSED_PAD src0_sel:WORD_1 src1_sel:DWORD
	v_and_b32_sdwa v57, v54, v82 dst_sel:DWORD dst_unused:UNUSED_PAD src0_sel:WORD_1 src1_sel:DWORD
	v_add3_u32 v55, v55, v56, s7
	v_add3_u32 v54, v54, v57, s7
	v_lshrrev_b32_e32 v55, 16, v55
	v_and_or_b32 v54, v54, s9, v55
	global_store_dword v[48:49], v54, off
	v_lshl_add_u64 v[48:49], v[48:49], 0, s[14:15]
	s_cselect_b32 s62, 1, 0
	s_add_i32 s61, s61, 1
	s_waitcnt lgkmcnt(0)
	v_mov_b32_e32 v226, s61
	s_mov_b64 s[58:59], exec
	s_mov_b64 exec, 1
	ds_write_b32 v224, v226
	s_mov_b64 exec, s[58:59]
	s_sub_i32 s63, s61, 1

.Lst_go_3:
	s_cmp_lg_u32 s62, 0
	s_cbranch_vccnz .LBB0_675

.LBB0_669:
	ds_read_b128 v[120:123], v168 offset:39680
	ds_read_b128 v[124:127], v169 offset:39680
	ds_read_b128 v[128:131], v170 offset:39680
	ds_read_b128 v[132:135], v171 offset:39680
	ds_read_b128 v[136:139], v172 offset:39680
	ds_read_b128 v[140:143], v173 offset:39680
	ds_read_b128 v[144:147], v174 offset:39680
	ds_read_b128 v[148:151], v175 offset:39680
	s_cmpk_gt_u32 s13, 0x1fd
	s_cselect_b64 s[16:17], -1, 0
	s_nop 0
	s_nop 0
	s_nop 0
	s_waitcnt lgkmcnt(0)
	v_pk_add_f32 v[120:121], v[120:121], v[124:125]
	v_pk_add_f32 v[122:123], v[122:123], v[126:127]
	v_pk_add_f32 v[128:129], v[128:129], v[132:133]
	v_pk_add_f32 v[130:131], v[130:131], v[134:135]
	v_pk_add_f32 v[120:121], v[120:121], v[128:129]
	v_pk_add_f32 v[122:123], v[122:123], v[130:131]
	v_pk_add_f32 v[120:121], v[120:121], v[122:123]
	v_add_f32_e32 v120, v120, v121
	v_pk_add_f32 v[136:137], v[136:137], v[140:141]
	v_pk_add_f32 v[138:139], v[138:139], v[142:143]
	v_pk_add_f32 v[144:145], v[144:145], v[148:149]
	v_pk_add_f32 v[146:147], v[146:147], v[150:151]
	v_pk_add_f32 v[136:137], v[136:137], v[144:145]
	v_pk_add_f32 v[138:139], v[138:139], v[146:147]
	v_pk_add_f32 v[136:137], v[136:137], v[138:139]
	v_add_f32_e32 v136, v136, v137
	v_bfi_b32 v61, v176, v136, v120
	v_bfi_b32 v60, v176, v120, v136
	v_and_b32_sdwa v62, v61, v82 dst_sel:DWORD dst_unused:UNUSED_PAD src0_sel:WORD_1 src1_sel:DWORD
	v_and_b32_sdwa v63, v60, v82 dst_sel:DWORD dst_unused:UNUSED_PAD src0_sel:WORD_1 src1_sel:DWORD
	v_add3_u32 v61, v61, v62, s7
	v_add3_u32 v60, v60, v63, s7
	v_lshrrev_b32_e32 v61, 16, v61
	v_and_or_b32 v62, v60, s9, v61
	v_add_co_u32_e32 v60, vcc, 0xfffe0000, v48
	s_nop 1
	v_addc_co_u32_e32 v61, vcc, -1, v49, vcc
	s_and_b64 vcc, exec, s[16:17]
	global_store_dword v[60:61], v62, off
	s_cselect_b32 s62, 1, 0
	s_add_i32 s61, s61, 1
	s_waitcnt lgkmcnt(0)
	v_mov_b32_e32 v226, s61
	s_mov_b64 s[58:59], exec
	s_mov_b64 exec, 1
	ds_write_b32 v224, v226
	s_mov_b64 exec, s[58:59]
	s_sub_i32 s63, s61, 1

.Lst_go_4:
	s_cmp_lg_u32 s62, 0
	s_cbranch_vccnz .LBB0_673
	s_waitcnt vmcnt(11)
	v_cvt_f32_f16_sdwa v65, v30 dst_sel:DWORD dst_unused:UNUSED_PAD src0_sel:WORD_1
	v_cvt_f32_f16_e32 v64, v30
	s_waitcnt vmcnt(6)
	v_cvt_f32_f16_sdwa v63, v38 dst_sel:DWORD dst_unused:UNUSED_PAD src0_sel:WORD_1
	v_cvt_f32_f16_e32 v62, v38
	v_cvt_f32_f16_sdwa v67, v31 dst_sel:DWORD dst_unused:UNUSED_PAD src0_sel:WORD_1
	v_pk_add_f32 v[84:85], v[64:65], 1.0 op_sel_hi:[1,0] neg_lo:[1,0] neg_hi:[1,0]
	v_cvt_f32_f16_sdwa v65, v39 dst_sel:DWORD dst_unused:UNUSED_PAD src0_sel:WORD_1
	v_cvt_f32_f16_e32 v64, v39
	v_cvt_f32_f16_e32 v66, v31
	v_cvt_f32_f16_sdwa v93, v40 dst_sel:DWORD dst_unused:UNUSED_PAD src0_sel:WORD_1
	v_cvt_f32_f16_e32 v92, v40
	s_waitcnt vmcnt(4)
	v_cvt_f32_f16_sdwa v95, v46 dst_sel:DWORD dst_unused:UNUSED_PAD src0_sel:WORD_1
	v_cvt_f32_f16_e32 v94, v46
	v_cvt_f32_f16_sdwa v103, v47 dst_sel:DWORD dst_unused:UNUSED_PAD src0_sel:WORD_1
	v_cvt_f32_f16_e32 v102, v47
	v_cvt_f32_f16_sdwa v105, v41 dst_sel:DWORD dst_unused:UNUSED_PAD src0_sel:WORD_1
	v_cvt_f32_f16_e32 v104, v41
	v_cvt_f32_f16_sdwa v61, v34 dst_sel:DWORD dst_unused:UNUSED_PAD src0_sel:WORD_1
	v_cvt_f32_f16_e32 v60, v34
	v_pk_add_f32 v[88:89], v[62:63], 1.0 op_sel_hi:[1,0] neg_lo:[1,0] neg_hi:[1,0]
	v_cvt_f32_f16_sdwa v91, v28 dst_sel:DWORD dst_unused:UNUSED_PAD src0_sel:WORD_1
	v_cvt_f32_f16_e32 v90, v28
	v_cvt_f32_f16_sdwa v63, v35 dst_sel:DWORD dst_unused:UNUSED_PAD src0_sel:WORD_1
	v_cvt_f32_f16_e32 v62, v35
	v_cvt_f32_f16_sdwa v101, v29 dst_sel:DWORD dst_unused:UNUSED_PAD src0_sel:WORD_1
	v_cvt_f32_f16_e32 v100, v29
	v_pk_add_f32 v[98:99], v[64:65], 1.0 op_sel_hi:[1,0] neg_lo:[1,0] neg_hi:[1,0]
	v_pk_add_f32 v[86:87], v[66:67], 1.0 op_sel_hi:[1,0] neg_lo:[1,0] neg_hi:[1,0]
	v_pk_mul_f32 v[96:97], v[88:89], v[92:93]
	v_pk_mul_f32 v[68:69], v[84:85], v[94:95]
	v_pk_mul_f32 v[70:71], v[86:87], v[102:103]
	v_pk_mul_f32 v[106:107], v[98:99], v[104:105]
	v_pk_mul_f32 v[64:65], v[84:85], v[90:91]
	v_pk_mul_f32 v[66:67], v[86:87], v[100:101]
	v_pk_mul_f32 v[72:73], v[84:85], v[96:97]
	v_pk_mul_f32 v[74:75], v[86:87], v[106:107]
	v_pk_mul_f32 v[84:85], v[84:85], v[88:89]
	v_pk_mul_f32 v[86:87], v[86:87], v[98:99]
	v_mov_b32_e32 v120, v60
	v_mov_b32_e32 v121, v68
	v_mov_b32_e32 v122, v61
	v_mov_b32_e32 v123, v69
	v_mov_b32_e32 v124, v64
	v_mov_b32_e32 v125, v72
	v_mov_b32_e32 v126, v65
	v_mov_b32_e32 v127, v73
	v_mov_b32_e32 v128, v62
	v_mov_b32_e32 v129, v70
	v_mov_b32_e32 v130, v63
	v_mov_b32_e32 v131, v71
	v_mov_b32_e32 v132, v66
	v_mov_b32_e32 v133, v74
	v_mov_b32_e32 v134, v67
	v_mov_b32_e32 v135, v75
	ds_write_b128 v80, v[84:87] offset:1024
	v_cvt_f32_f16_e32 v68, v36
	v_cvt_f32_f16_sdwa v70, v36 dst_sel:DWORD dst_unused:UNUSED_PAD src0_sel:WORD_1
	v_cvt_f32_f16_e32 v69, v32
	v_cvt_f32_f16_sdwa v71, v32 dst_sel:DWORD dst_unused:UNUSED_PAD src0_sel:WORD_1
	v_cvt_f32_f16_e32 v75, v33
	v_cvt_f32_f16_sdwa v85, v33 dst_sel:DWORD dst_unused:UNUSED_PAD src0_sel:WORD_1
	v_cvt_f32_f16_e32 v74, v37
	v_cvt_f32_f16_sdwa v84, v37 dst_sel:DWORD dst_unused:UNUSED_PAD src0_sel:WORD_1
	v_mov_b32_e32 v62, v68
	v_mov_b32_e32 v63, v70
	v_mov_b32_e32 v60, v69
	v_mov_b32_e32 v61, v71
	v_pk_mul_f32 v[64:65], v[88:89], v[62:63]
	v_mov_b32_e32 v62, v75
	v_mov_b32_e32 v63, v85
	v_pk_mul_f32 v[60:61], v[88:89], v[60:61]
	v_pk_mul_f32 v[62:63], v[98:99], v[62:63]
	v_mov_b32_e32 v66, v74
	v_mov_b32_e32 v67, v84
	v_mov_b32_e32 v72, v95
	v_pk_mul_f32 v[66:67], v[98:99], v[66:67]
	v_mov_b32_e32 v182, v60
	v_mov_b32_e32 v183, v61
	v_mov_b32_e32 v184, v62
	v_mov_b32_e32 v185, v63
	ds_write_b128 v80, v[64:67] offset:1536
	v_pk_fma_f32 v[60:61], v[94:95], v[68:69], 0 op_sel_hi:[0,1,0]
	v_pk_fma_f32 v[60:61], v[72:73], v[70:71], v[60:61] op_sel_hi:[0,1,1]
	v_mov_b32_e32 v64, v91
	v_pk_fma_f32 v[72:73], v[90:91], v[68:69], 0 op_sel_hi:[0,1,0]
	v_pk_fma_f32 v[68:69], v[96:97], v[68:69], 0 op_sel_hi:[0,1,0]
	v_pk_fma_f32 v[64:65], v[64:65], v[70:71], v[72:73] op_sel_hi:[0,1,1]
	v_pk_fma_f32 v[68:69], v[96:97], v[70:71], v[68:69] op_sel:[1,0,0]
	v_mov_b32_e32 v86, v103
	v_pk_fma_f32 v[60:61], v[102:103], v[74:75], v[60:61] op_sel_hi:[0,1,1]
	v_mov_b32_e32 v66, v101
	v_pk_fma_f32 v[64:65], v[100:101], v[74:75], v[64:65] op_sel_hi:[0,1,1]
	v_pk_fma_f32 v[68:69], v[106:107], v[74:75], v[68:69] op_sel_hi:[0,1,1]
	v_pk_fma_f32 v[60:61], v[86:87], v[84:85], v[60:61] op_sel_hi:[0,1,1]
	v_pk_fma_f32 v[64:65], v[66:67], v[84:85], v[64:65] op_sel_hi:[0,1,1]
	v_pk_fma_f32 v[68:69], v[106:107], v[84:85], v[68:69] op_sel:[1,0,0]
	v_cvt_f32_f16_e32 v85, v42
	v_cvt_f32_f16_sdwa v87, v42 dst_sel:DWORD dst_unused:UNUSED_PAD src0_sel:WORD_1
	v_cvt_f32_f16_e32 v91, v43
	v_cvt_f32_f16_sdwa v95, v43 dst_sel:DWORD dst_unused:UNUSED_PAD src0_sel:WORD_1
	s_waitcnt vmcnt(3)
	v_cvt_f32_f16_e32 v84, v44
	v_cvt_f32_f16_sdwa v86, v44 dst_sel:DWORD dst_unused:UNUSED_PAD src0_sel:WORD_1
	v_cvt_f32_f16_e32 v90, v45
	v_cvt_f32_f16_sdwa v94, v45 dst_sel:DWORD dst_unused:UNUSED_PAD src0_sel:WORD_1
	v_mov_b32_e32 v72, v85
	v_mov_b32_e32 v73, v87
	v_mov_b32_e32 v74, v91
	v_mov_b32_e32 v75, v95
	ds_write_b128 v80, v[72:75] offset:1792
	v_mov_b32_e32 v72, v84
	v_mov_b32_e32 v73, v86
	v_mov_b32_e32 v74, v90
	v_mov_b32_e32 v75, v94
	v_mov_b32_e32 v88, v93
	ds_write_b128 v80, v[72:75] offset:2048
	v_mov_b32_e32 v186, v72
	v_mov_b32_e32 v187, v73
	v_mov_b32_e32 v188, v74
	v_mov_b32_e32 v189, v75
	v_pk_fma_f32 v[72:73], v[92:93], v[84:85], 0 op_sel_hi:[0,1,0]
	v_pk_fma_f32 v[72:73], v[88:89], v[86:87], v[72:73] op_sel_hi:[0,1,1]
	v_mov_b32_e32 v96, v105
	v_pk_fma_f32 v[72:73], v[104:105], v[90:91], v[72:73] op_sel_hi:[0,1,1]
	v_pk_fma_f32 v[72:73], v[96:97], v[94:95], v[72:73] op_sel_hi:[0,1,1]
	v_mov_b32_dpp v62, v60 row_ror:8 row_mask:0xf bank_mask:0xf bound_ctrl:1
	v_mov_b32_dpp v63, v61 row_ror:8 row_mask:0xf bank_mask:0xf bound_ctrl:1
	v_mov_b32_dpp v66, v64 row_ror:8 row_mask:0xf bank_mask:0xf bound_ctrl:1
	v_mov_b32_dpp v67, v65 row_ror:8 row_mask:0xf bank_mask:0xf bound_ctrl:1
	v_mov_b32_dpp v70, v68 row_ror:8 row_mask:0xf bank_mask:0xf bound_ctrl:1
	v_mov_b32_dpp v71, v69 row_ror:8 row_mask:0xf bank_mask:0xf bound_ctrl:1
	v_mov_b32_dpp v74, v72 row_ror:8 row_mask:0xf bank_mask:0xf bound_ctrl:1
	v_mov_b32_dpp v75, v73 row_ror:8 row_mask:0xf bank_mask:0xf bound_ctrl:1
	v_pk_add_f32 v[60:61], v[60:61], v[62:63]
	v_pk_add_f32 v[64:65], v[64:65], v[66:67]
	v_pk_add_f32 v[68:69], v[68:69], v[70:71]
	v_pk_add_f32 v[72:73], v[72:73], v[74:75]
	v_mov_b32_dpp v62, v60 row_ror:4 row_mask:0xf bank_mask:0xf bound_ctrl:1
	v_mov_b32_dpp v63, v61 row_ror:4 row_mask:0xf bank_mask:0xf bound_ctrl:1
	v_mov_b32_dpp v66, v64 row_ror:4 row_mask:0xf bank_mask:0xf bound_ctrl:1
	v_mov_b32_dpp v67, v65 row_ror:4 row_mask:0xf bank_mask:0xf bound_ctrl:1
	v_mov_b32_dpp v70, v68 row_ror:4 row_mask:0xf bank_mask:0xf bound_ctrl:1
	v_mov_b32_dpp v71, v69 row_ror:4 row_mask:0xf bank_mask:0xf bound_ctrl:1
	v_mov_b32_dpp v74, v72 row_ror:4 row_mask:0xf bank_mask:0xf bound_ctrl:1
	v_mov_b32_dpp v75, v73 row_ror:4 row_mask:0xf bank_mask:0xf bound_ctrl:1
	v_pk_add_f32 v[60:61], v[60:61], v[62:63]
	v_pk_add_f32 v[64:65], v[64:65], v[66:67]
	v_pk_add_f32 v[68:69], v[68:69], v[70:71]
	v_pk_add_f32 v[72:73], v[72:73], v[74:75]
	v_mov_b32_dpp v62, v60 row_ror:2 row_mask:0xf bank_mask:0xf bound_ctrl:1
	v_mov_b32_dpp v63, v61 row_ror:2 row_mask:0xf bank_mask:0xf bound_ctrl:1
	v_mov_b32_dpp v66, v64 row_ror:2 row_mask:0xf bank_mask:0xf bound_ctrl:1
	v_mov_b32_dpp v67, v65 row_ror:2 row_mask:0xf bank_mask:0xf bound_ctrl:1
	v_mov_b32_dpp v70, v68 row_ror:2 row_mask:0xf bank_mask:0xf bound_ctrl:1
	v_mov_b32_dpp v71, v69 row_ror:2 row_mask:0xf bank_mask:0xf bound_ctrl:1
	v_mov_b32_dpp v74, v72 row_ror:2 row_mask:0xf bank_mask:0xf bound_ctrl:1
	v_mov_b32_dpp v75, v73 row_ror:2 row_mask:0xf bank_mask:0xf bound_ctrl:1
	v_pk_add_f32 v[60:61], v[60:61], v[62:63]
	v_pk_add_f32 v[64:65], v[64:65], v[66:67]
	v_pk_add_f32 v[68:69], v[68:69], v[70:71]
	v_pk_add_f32 v[72:73], v[72:73], v[74:75]
	v_mov_b32_dpp v62, v60 row_ror:1 row_mask:0xf bank_mask:0xf bound_ctrl:1
	v_mov_b32_dpp v63, v61 row_ror:1 row_mask:0xf bank_mask:0xf bound_ctrl:1
	v_mov_b32_dpp v66, v64 row_ror:1 row_mask:0xf bank_mask:0xf bound_ctrl:1
	v_mov_b32_dpp v67, v65 row_ror:1 row_mask:0xf bank_mask:0xf bound_ctrl:1
	v_mov_b32_dpp v70, v68 row_ror:1 row_mask:0xf bank_mask:0xf bound_ctrl:1
	v_mov_b32_dpp v71, v69 row_ror:1 row_mask:0xf bank_mask:0xf bound_ctrl:1
	v_mov_b32_dpp v74, v72 row_ror:1 row_mask:0xf bank_mask:0xf bound_ctrl:1
	v_mov_b32_dpp v75, v73 row_ror:1 row_mask:0xf bank_mask:0xf bound_ctrl:1
	s_and_saveexec_b64 s[18:19], s[0:1]
	s_cbranch_execz .LBB0_672
	v_pk_add_f32 v[60:61], v[60:61], v[62:63]
	v_pk_add_f32 v[62:63], v[64:65], v[66:67]
	s_nop 0
	v_pk_mul_f32 v[62:63], v[62:63], s[12:13] op_sel_hi:[1,0]
	ds_write_b128 v77, v[60:63] offset:36864
	v_pk_add_f32 v[60:61], v[68:69], v[70:71]
	v_pk_add_f32 v[62:63], v[72:73], v[74:75]
	v_pk_mul_f32 v[60:61], v[60:61], s[12:13] op_sel_hi:[1,0]
	v_pk_mul_f32 v[62:63], v[62:63], s[12:13] op_sel_hi:[1,0]
	ds_write_b128 v77, v[60:63] offset:36880
